# attention: first step of every item goes straight to the original (max-based) code instead of failing the row-sum test first (scalar flag), on top of the row-sum test loop
# speedup vs baseline: 1.0183x; 1.0028x over previous
; DI float bflo(unsigned u) { return __uint_as_float(u << 16); }
; DI float bfhi(unsigned u) { return __uint_as_float(u & 0xffff0000u); }
; DI f32x16 zero16() { f32x16 z; for (int i = 0; i < 16; ++i) z[i] = 0.f; return z; }
; DI void phase_attn(const Params& p, int hf, bool skipctx, char* smem, int& rot) {
;     ...
;       uint4 qu[6];
; #pragma unroll
;       for (int ks = 0; ks < 6; ++ks) qu[ks] = *(const uint4*)(Qb + tq * 768 + head * 96 + ks * 16 + h * 8);
; #pragma unroll
;       for (int ks = 0; ks < 4; ++ks) {
;         const uint4 u = qu[ks];
;         qf[ks] = pack8(bflo(u.x) * QSCALE, bfhi(u.x) * QSCALE, bflo(u.y) * QSCALE, bfhi(u.y) * QSCALE, bflo(u.z) * QSCALE, bfhi(u.z) * QSCALE, bflo(u.w) * QSCALE, bfhi(u.w) * QSCALE);
;       }
;       const unsigned a1[4] = {qu[4].x, qu[4].y, qu[4].z, qu[4].w}, a2[4] = {qu[5].x, qu[5].y, qu[5].z, qu[5].w};
;       float o1[8], o2[8];
;       const int sq_ = s0 + w * 32 + r;
; #pragma unroll
;       for (int e = 0; e < 8; ++e) {
;         const float x1 = ((e & 1) ? bfhi(a1[e >> 1]) : bflo(a1[e >> 1])) * QSCALE;
;         const float x2 = ((e & 1) ? bfhi(a2[e >> 1]) : bflo(a2[e >> 1])) * QSCALE;
;         float cs = 1.f, sn = 0.f;
;         if (sq_ >= LC) { cs = axc[(sq_ - LC) * 16 + 8 * h + e]; sn = axs[(sq_ - LC) * 16 + 8 * h + e]; }
;         o1[e] = x1 * cs - x2 * sn; o2[e] = x1 * sn + x2 * cs;
;       }
;       qf[4] = pack8(o1[0], o1[1], o1[2], o1[3], o1[4], o1[5], o1[6], o1[7]);
;       qf[5] = pack8(o2[0], o2[1], o2[2], o2[3], o2[4], o2[5], o2[6], o2[7]);
;     }
;     const bf16_t* Kg = Kb + (size_t)(bl * 8 + head) * S * 96;
;     const bf16_t* Vg = VTb + (size_t)(bl * 8 + head) * 64 * S;
;     f32x16 o[2]; o[0] = zero16(); o[1] = zero16();
;     float m_run = -1e30f, l_run = 0.f;
;     uint4 ak0, ak1, ak2, av0, av1, bk0, bk1, bk2, bv0, bv1;
;     const int kr0 = tid / 12, kc0 = tid - kr0 * 12, kr1 = (tid + 512) / 12, kc1 = (tid + 512) - kr1 * 12, kr2 = (tid + 1024) / 12, kc2 = (tid + 1024) - kr2 * 12;
.LBB0_794:
	s_or_b64 exec, exec, s[26:27]
	s_waitcnt vmcnt(0)
	v_lshlrev_b32_e32 v27, 16, v23
	v_lshlrev_b32_e32 v26, 16, v19
	v_pk_mul_f32 v[26:27], v[26:27], s[48:49] op_sel_hi:[1,0]
	v_lshlrev_b32_e32 v47, 16, v22
	v_pk_mul_f32 v[28:29], v[26:27], v[30:31] op_sel:[0,1] op_sel_hi:[1,0]
	v_pk_mul_f32 v[26:27], v[26:27], v[30:31]
	v_and_b32_e32 v30, 0xffff0000, v19
	v_lshlrev_b32_e32 v46, 16, v18
	v_and_b32_e32 v19, 0xffff0000, v22
	v_and_b32_e32 v18, 0xffff0000, v18
	v_and_b32_e32 v31, 0xffff0000, v23
	v_pk_mul_f32 v[46:47], v[46:47], s[48:49] op_sel_hi:[1,0]
	v_pk_mul_f32 v[22:23], v[18:19], s[48:49] op_sel_hi:[1,0]
	v_pk_mul_f32 v[48:49], v[46:47], v[42:43] op_sel:[0,1] op_sel_hi:[1,0]
	v_pk_mul_f32 v[42:43], v[46:47], v[42:43]
	v_pk_mul_f32 v[18:19], v[22:23], v[40:41] op_sel:[0,1] op_sel_hi:[1,0]
	v_pk_mul_f32 v[22:23], v[22:23], v[40:41]
	v_mov_b32_e32 v40, v42
	v_mov_b32_e32 v41, v22
	v_mov_b32_e32 v22, v43
	v_pk_add_f32 v[22:23], v[40:41], v[22:23]
	v_lshlrev_b32_e32 v41, 16, v21
	v_lshlrev_b32_e32 v40, 16, v17
	v_pk_mul_f32 v[40:41], v[40:41], s[48:49] op_sel_hi:[1,0]
	v_mov_b32_e32 v46, v48
	v_mov_b32_e32 v47, v18
	v_mov_b32_e32 v18, v49
	v_pk_mul_f32 v[42:43], v[40:41], v[32:33] op_sel:[0,1] op_sel_hi:[1,0]
	v_pk_mul_f32 v[40:41], v[40:41], v[32:33]
	v_and_b32_e32 v33, 0xffff0000, v21
	v_and_b32_e32 v32, 0xffff0000, v17
	v_pk_add_f32 v[18:19], v[46:47], v[18:19] neg_lo:[0,1] neg_hi:[0,1]
	v_pk_mul_f32 v[46:47], v[32:33], s[48:49] op_sel_hi:[1,0]
	v_mov_b32_e32 v48, v42
	v_pk_mul_f32 v[32:33], v[46:47], v[34:35] op_sel:[0,1] op_sel_hi:[1,0]
	v_pk_mul_f32 v[34:35], v[46:47], v[34:35]
	v_mov_b32_e32 v49, v32
	v_mov_b32_e32 v32, v43
	v_mov_b32_e32 v42, v40
	v_mov_b32_e32 v43, v34
	v_mov_b32_e32 v34, v41
	v_lshlrev_b32_e32 v41, 16, v20
	v_lshlrev_b32_e32 v40, 16, v16
	v_and_b32_e32 v17, 0xffff0000, v20
	v_and_b32_e32 v16, 0xffff0000, v16
	v_pk_mul_f32 v[40:41], v[40:41], s[48:49] op_sel_hi:[1,0]
	v_pk_mul_f32 v[20:21], v[16:17], s[48:49] op_sel_hi:[1,0]
	v_pk_add_f32 v[34:35], v[42:43], v[34:35]
	v_pk_mul_f32 v[42:43], v[40:41], v[38:39] op_sel:[0,1] op_sel_hi:[1,0]
	v_pk_mul_f32 v[38:39], v[40:41], v[38:39]
	v_pk_mul_f32 v[16:17], v[20:21], v[36:37] op_sel:[0,1] op_sel_hi:[1,0]
	v_pk_mul_f32 v[20:21], v[20:21], v[36:37]
	v_mov_b32_e32 v36, v38
	v_mov_b32_e32 v37, v20
	v_mov_b32_e32 v20, v39
	v_pk_add_f32 v[20:21], v[36:37], v[20:21]
	v_lshlrev_b32_e32 v36, 16, v12
	v_and_b32_e32 v37, 0xffff0000, v12
	v_lshlrev_b32_e32 v12, 16, v13
	v_and_b32_e32 v13, 0xffff0000, v13
	v_pk_mul_f32 v[12:13], v[12:13], s[48:49] op_sel_hi:[1,0]
	v_lshlrev_b32_e32 v38, 16, v14
	v_cvt_pk_bf16_f32 v65, v12, v13
	v_lshlrev_b32_e32 v12, 16, v8
	v_and_b32_e32 v13, 0xffff0000, v8
	v_lshlrev_b32_e32 v8, 16, v9
	v_and_b32_e32 v9, 0xffff0000, v9
	v_pk_mul_f32 v[8:9], v[8:9], s[48:49] op_sel_hi:[1,0]
	v_and_b32_e32 v39, 0xffff0000, v14
	v_cvt_pk_bf16_f32 v69, v8, v9
	v_lshlrev_b32_e32 v8, 16, v4
	v_and_b32_e32 v9, 0xffff0000, v4
	v_lshlrev_b32_e32 v4, 16, v5
	v_and_b32_e32 v5, 0xffff0000, v5
	v_lshlrev_b32_e32 v14, 16, v15
	v_and_b32_e32 v15, 0xffff0000, v15
	v_pk_mul_f32 v[4:5], v[4:5], s[48:49] op_sel_hi:[1,0]
	s_mov_b32 s16, 0x2aaaaaab
	v_pk_mul_f32 v[14:15], v[14:15], s[48:49] op_sel_hi:[1,0]
	v_cvt_pk_bf16_f32 v73, v4, v5
	v_mul_hi_i32 v4, v160, s16
	v_cvt_pk_bf16_f32 v67, v14, v15
	v_lshlrev_b32_e32 v14, 16, v10
	v_and_b32_e32 v15, 0xffff0000, v10
	v_lshlrev_b32_e32 v10, 16, v11
	v_and_b32_e32 v11, 0xffff0000, v11
	v_lshrrev_b32_e32 v5, 31, v4
	v_ashrrev_i32_e32 v4, 1, v4
	v_pk_mul_f32 v[10:11], v[10:11], s[48:49] op_sel_hi:[1,0]
	v_add_u32_e32 v45, v4, v5
	v_cvt_pk_bf16_f32 v71, v10, v11
	v_lshlrev_b32_e32 v10, 16, v6
	v_and_b32_e32 v11, 0xffff0000, v6
	v_lshlrev_b32_e32 v6, 16, v7
	v_and_b32_e32 v7, 0xffff0000, v7
	v_mad_u64_u32 v[4:5], s[38:39], v45, -12, v[160:161]
	v_add_u32_e32 v164, 0x200, v160
	v_pk_mul_f32 v[6:7], v[6:7], s[48:49] op_sel_hi:[1,0]
	v_mul_hi_i32 v5, v164, s16
	v_cvt_pk_bf16_f32 v75, v6, v7
	v_lshrrev_b32_e32 v6, 31, v5
	v_ashrrev_i32_e32 v5, 1, v5
	s_mul_i32 s15, s4, 0xcc000
	v_add_u32_e32 v5, v5, v6
	v_pk_mul_f32 v[38:39], v[38:39], s[48:49] op_sel_hi:[1,0]
	v_pk_mul_f32 v[14:15], v[14:15], s[48:49] op_sel_hi:[1,0]
	s_mul_hi_i32 s5, s4, 0xcc000
	s_add_u32 s26, s90, s15
	v_mad_u64_u32 v[6:7], s[38:39], v5, -12, v[164:165]
	v_add_u32_e32 v162, 0x400, v160
	v_cvt_pk_bf16_f32 v66, v38, v39
	v_cvt_pk_bf16_f32 v70, v14, v15
	v_pk_mul_f32 v[8:9], v[8:9], s[48:49] op_sel_hi:[1,0]
	v_pk_mul_f32 v[10:11], v[10:11], s[48:49] op_sel_hi:[1,0]
	s_addc_u32 s27, s91, s5
	v_mul_hi_i32 v7, v162, s16
	v_lshlrev_b32_e32 v14, 3, v4
	v_lshlrev_b32_e32 v38, 3, v6
	v_pk_mul_f32 v[36:37], v[36:37], s[48:49] op_sel_hi:[1,0]
	v_pk_mul_f32 v[12:13], v[12:13], s[48:49] op_sel_hi:[1,0]
	v_cvt_pk_bf16_f32 v72, v8, v9
	v_cvt_pk_bf16_f32 v74, v10, v11
	v_lshrrev_b32_e32 v8, 31, v7
	v_ashrrev_i32_e32 v7, 1, v7
	v_mov_b64_e32 v[10:11], s[26:27]
	v_ashrrev_i32_e32 v15, 31, v14
	v_ashrrev_i32_e32 v39, 31, v38
	v_cvt_pk_bf16_f32 v64, v36, v37
	v_cvt_pk_bf16_f32 v68, v12, v13
	v_add_u32_e32 v7, v7, v8
	v_mad_i64_i32 v[12:13], s[26:27], v45, s17, v[10:11]
	v_lshlrev_b64 v[14:15], 1, v[14:15]
	v_mad_i64_i32 v[36:37], s[26:27], v5, s17, v[10:11]
	v_lshlrev_b64 v[38:39], 1, v[38:39]
	v_mad_u64_u32 v[8:9], s[38:39], v7, -12, v[162:163]
	v_lshl_add_u64 v[12:13], v[12:13], 0, v[14:15]
	v_lshl_add_u64 v[36:37], v[36:37], 0, v[38:39]
	s_barrier
; DI float bflo(unsigned u) { return __uint_as_float(u << 16); }
; DI float bfhi(unsigned u) { return __uint_as_float(u & 0xffff0000u); }
; DI f32x16 zero16() { f32x16 z; for (int i = 0; i < 16; ++i) z[i] = 0.f; return z; }
; DI void phase_attn(const Params& p, int hf, bool skipctx, char* smem, int& rot) {
;     ...
;       const unsigned a1[4] = {qu[4].x, qu[4].y, qu[4].z, qu[4].w}, a2[4] = {qu[5].x, qu[5].y, qu[5].z, qu[5].w};
;       float o1[8], o2[8];
;       const int sq_ = s0 + w * 32 + r;
; #pragma unroll
;       for (int e = 0; e < 8; ++e) {
;         const float x1 = ((e & 1) ? bfhi(a1[e >> 1]) : bflo(a1[e >> 1])) * QSCALE;
;         const float x2 = ((e & 1) ? bfhi(a2[e >> 1]) : bflo(a2[e >> 1])) * QSCALE;
;         float cs = 1.f, sn = 0.f;
;         if (sq_ >= LC) { cs = axc[(sq_ - LC) * 16 + 8 * h + e]; sn = axs[(sq_ - LC) * 16 + 8 * h + e]; }
;         o1[e] = x1 * cs - x2 * sn; o2[e] = x1 * sn + x2 * cs;
;       }
;       qf[4] = pack8(o1[0], o1[1], o1[2], o1[3], o1[4], o1[5], o1[6], o1[7]);
;       qf[5] = pack8(o2[0], o2[1], o2[2], o2[3], o2[4], o2[5], o2[6], o2[7]);
;     }
;     const bf16_t* Kg = Kb + (size_t)(bl * 8 + head) * S * 96;
;     const bf16_t* Vg = VTb + (size_t)(bl * 8 + head) * 64 * S;
;     f32x16 o[2]; o[0] = zero16(); o[1] = zero16();
;     float m_run = -1e30f, l_run = 0.f;
;     uint4 ak0, ak1, ak2, av0, av1, bk0, bk1, bk2, bv0, bv1;
;     const int kr0 = tid / 12, kc0 = tid - kr0 * 12, kr1 = (tid + 512) / 12, kc1 = (tid + 512) - kr1 * 12, kr2 = (tid + 1024) / 12, kc2 = (tid + 1024) - kr2 * 12;
;     const int vr0 = tid >> 4, vr1 = (tid + 512) >> 4, vc = tid & 15;
	global_load_dwordx4 v[76:79], v[12:13], off
	global_load_dwordx4 v[80:83], v[36:37], off
	v_lshlrev_b32_e32 v36, 3, v8
	s_mul_i32 s15, s4, 0x88000
	v_readlane_b32 s36, v252, 5
	v_ashrrev_i32_e32 v37, 31, v36
	s_mul_hi_i32 s5, s4, 0x88000
	v_readlane_b32 s37, v252, 6
	s_add_u32 s36, s36, s15
	v_mad_i64_i32 v[12:13], s[26:27], v7, s17, v[10:11]
	v_lshlrev_b64 v[36:37], 1, v[36:37]
	s_addc_u32 s37, s37, s5
	v_lshl_add_u64 v[12:13], v[12:13], 0, v[36:37]
	v_mov_b32_e32 v40, v42
	v_mov_b32_e32 v41, v16
	v_mov_b32_e32 v16, v43
	v_ashrrev_i32_e32 v9, 4, v160
	v_ashrrev_i32_e32 v50, 4, v164
	global_load_dwordx4 v[84:87], v[12:13], off
	v_mov_b64_e32 v[12:13], s[36:37]
	s_movk_i32 s16, 0x2200
	v_lshlrev_b32_e32 v165, 4, v160
	v_cvt_pk_bf16_f32 v100, v20, v21
	v_add_u32_e32 v20, 0x80, v5
	v_pk_add_f32 v[16:17], v[40:41], v[16:17] neg_lo:[0,1] neg_hi:[0,1]
	v_mad_i64_i32 v[40:41], s[26:27], v9, s16, v[12:13]
	v_and_b32_e32 v42, 0xf0, v165
	v_mov_b32_e32 v43, v221
	v_mad_i64_i32 v[12:13], s[26:27], v50, s16, v[12:13]
	v_cvt_pk_bf16_f32 v98, v18, v19
	v_cvt_pk_bf16_f32 v102, v22, v23
	v_add_u32_e32 v18, 0x80, v45
	v_mad_i64_i32 v[20:21], s[26:27], v20, s17, v[10:11]
	v_add_u32_e32 v22, 0x80, v7
	v_lshl_add_u64 v[40:41], v[40:41], 0, v[42:43]
	v_lshl_add_u64 v[12:13], v[12:13], 0, v[42:43]
	v_mad_i64_i32 v[18:19], s[26:27], v18, s17, v[10:11]
	v_lshl_add_u64 v[20:21], v[20:21], 0, v[38:39]
	v_mad_i64_i32 v[10:11], s[26:27], v22, s17, v[10:11]
	global_load_dwordx4 v[92:95], v[40:41], off
	global_load_dwordx4 v[104:107], v[12:13], off
	v_lshl_add_u64 v[18:19], v[18:19], 0, v[14:15]
	v_lshl_add_u64 v[10:11], v[10:11], 0, v[36:37]
	global_load_dwordx4 v[108:111], v[20:21], off
	global_load_dwordx4 v[116:119], v[10:11], off
	global_load_dwordx4 v[120:123], v[40:41], off offset:256
	global_load_dwordx4 v[112:115], v[18:19], off
	global_load_dwordx4 v[124:127], v[12:13], off offset:256
	v_lshlrev_b32_e32 v46, 16, v0
	v_and_b32_e32 v47, 0xffff0000, v0
	v_lshlrev_b32_e32 v0, 16, v1
	v_and_b32_e32 v1, 0xffff0000, v1
	v_pk_mul_f32 v[30:31], v[30:31], s[48:49] op_sel_hi:[1,0]
	v_pk_add_f32 v[32:33], v[48:49], v[32:33] neg_lo:[0,1] neg_hi:[0,1]
	v_pk_mul_f32 v[0:1], v[0:1], s[48:49] op_sel_hi:[1,0]
	v_lshlrev_b32_e32 v48, 16, v2
	v_and_b32_e32 v49, 0xffff0000, v2
	v_lshlrev_b32_e32 v2, 16, v3
	v_and_b32_e32 v3, 0xffff0000, v3
	v_pk_mul_f32 v[2:3], v[2:3], s[48:49] op_sel_hi:[1,0]
	v_cvt_pk_bf16_f32 v89, v0, v1
	v_pk_mul_f32 v[0:1], v[30:31], v[24:25] op_sel:[0,1] op_sel_hi:[1,0]
	v_cvt_pk_bf16_f32 v91, v2, v3
	v_mov_b32_e32 v2, v28
	v_mov_b32_e32 v3, v0
	v_mov_b32_e32 v0, v29
	v_pk_add_f32 v[0:1], v[2:3], v[0:1] neg_lo:[0,1] neg_hi:[0,1]
	v_pk_mul_f32 v[2:3], v[30:31], v[24:25]
	v_mul_lo_u32 v10, v45, s97
	v_mov_b32_e32 v24, v26
	v_mov_b32_e32 v25, v2
	v_mov_b32_e32 v2, v27
	v_add_u32_e32 v10, 0, v10
	v_lshlrev_b32_e32 v4, 4, v4
	v_pk_add_f32 v[2:3], v[24:25], v[2:3]
	v_add_u32_e32 v176, v10, v4
	v_mul_lo_u32 v4, v5, s97
	v_cvt_pk_bf16_f32 v103, v2, v3
	v_mad_i64_i32 v[2:3], s[26:27], v5, s17, 0
	v_add_u32_e32 v4, 0, v4
	v_lshlrev_b32_e32 v5, 4, v6
	v_add_u32_e32 v177, v4, v5
	v_mul_lo_u32 v4, v7, s97
	v_add_u32_e32 v4, 0, v4
	v_lshlrev_b32_e32 v5, 4, v8
	s_movk_i32 s20, 0x108
	v_cvt_pk_bf16_f32 v96, v16, v17
	v_cvt_pk_bf16_f32 v99, v0, v1
	v_mad_i64_i32 v[0:1], s[26:27], v45, s17, 0
	v_mad_i64_i32 v[16:17], s[26:27], v7, s17, 0
	v_add_u32_e32 v178, v4, v5
	v_mul_lo_u32 v4, v9, s20
	v_add_u32_e32 v5, 0, v4
	s_movk_i32 s26, 0x6800
	v_add3_u32 v179, v5, v42, s26
	v_mul_lo_u32 v5, v50, s20
	v_add_u32_e32 v6, 0, v5
	v_add3_u32 v180, v6, v42, s26
	v_or_b32_e32 v181, 32, v161
	v_or_b32_e32 v182, 64, v161
	v_or_b32_e32 v183, 0x60, v161
	v_readlane_b32 s26, v254, 35
	v_mul_u32_u24_e32 v19, 0x108, v44
	v_mad_u32_u24 v18, v44, s97, 0
	v_add_u32_e32 v21, s26, v4
	v_add_u32_e32 v22, s26, v5
	v_add_u32_e32 v23, s26, v161
	v_add_u32_e32 v24, s26, v181
	v_mov_b32_e32 v4, s26
	v_add_u32_e32 v25, s26, v182
	v_add_u32_e32 v26, s26, v183
	v_readlane_b32 s26, v254, 36
	v_mad_u32_u24 v184, v44, s20, v4
	v_add_u32_e32 v20, 0, v161
	v_add_u32_e32 v27, s26, v161
	v_add_u32_e32 v28, s26, v181
	v_mov_b32_e32 v4, s26
	v_add_u32_e32 v29, s26, v182
	v_add_u32_e32 v30, s26, v183
	s_add_u32 s26, s15, 0x1a49c300
	s_addc_u32 s27, s5, 0
	v_mad_u32_u24 v185, v44, s20, v4
	v_mov_b64_e32 v[4:5], s[26:27]
	v_mad_i64_i32 v[166:167], s[26:27], v9, s16, v[4:5]
	v_mad_i64_i32 v[168:169], s[26:27], v50, s16, v[4:5]
	v_mad_i64_i32 v[4:5], s[26:27], s4, v231, v[16:17]
	v_mad_i64_i32 v[2:3], s[26:27], s4, v231, v[2:3]
	v_mad_i64_i32 v[0:1], s[4:5], s4, v231, v[0:1]
	v_lshl_add_u64 v[174:175], v[0:1], 0, v[14:15]
	v_mov_b32_e32 v14, v221
	v_mov_b32_e32 v15, v221
	v_add_u32_e32 v186, v21, v42
	v_add_u32_e32 v187, v22, v42
	v_add_u32_e32 v188, v23, v19
	v_add_u32_e32 v16, v24, v19
	v_add_u32_e32 v17, v25, v19
	v_add_u32_e32 v21, v26, v19
	v_add_u32_e32 v22, v28, v19
	v_add_u32_e32 v23, v29, v19
	v_add_u32_e32 v24, v30, v19
	v_pk_mul_f32 v[46:47], v[46:47], s[48:49] op_sel_hi:[1,0]
	v_pk_mul_f32 v[48:49], v[48:49], s[48:49] op_sel_hi:[1,0]
	v_lshl_add_u64 v[170:171], v[4:5], 0, v[36:37]
	v_lshl_add_u64 v[172:173], v[2:3], 0, v[38:39]
	v_mov_b32_e32 v0, v221
	v_mov_b32_e32 v1, v221
	v_mov_b32_e32 v2, v221
	v_mov_b32_e32 v3, v221
	v_mov_b32_e32 v4, v221
	v_mov_b32_e32 v5, v221
	v_mov_b32_e32 v6, v221
	v_mov_b32_e32 v7, v221
	v_mov_b32_e32 v8, v221
	v_mov_b32_e32 v9, v221
	v_mov_b32_e32 v10, v221
	v_mov_b32_e32 v11, v221
	v_mov_b32_e32 v12, v221
	v_mov_b32_e32 v13, v221
	v_add_u32_e32 v189, v27, v19
	v_add_u32_e32 v190, v18, v220
	v_add_u32_e32 v191, v20, v19
	v_add_u32_e32 v194, 0x2000, v16
	v_add_u32_e32 v204, 0x2000, v17
	v_add_u32_e32 v206, 0x2000, v21
	v_add_u32_e32 v208, 0x2000, v22
	v_add_u32_e32 v210, 0x2000, v23
	v_add_u32_e32 v211, 0x2000, v24
	v_mov_b64_e32 v[30:31], v[14:15]
	v_cvt_pk_bf16_f32 v88, v46, v47
	v_cvt_pk_bf16_f32 v90, v48, v49
	v_cvt_pk_bf16_f32 v97, v32, v33
	v_cvt_pk_bf16_f32 v101, v34, v35
	v_or_b32_e32 v166, v166, v42
	v_or_b32_e32 v168, v168, v42
	s_mov_b32 s4, 0
	v_mov_b32_e32 v212, 0xf149f2ca
	v_mov_b32_e32 v213, 0
	v_mov_b64_e32 v[28:29], v[12:13]
	v_mov_b64_e32 v[26:27], v[10:11]
	v_mov_b64_e32 v[24:25], v[8:9]
	v_mov_b64_e32 v[22:23], v[6:7]
	v_mov_b64_e32 v[20:21], v[4:5]
	v_mov_b64_e32 v[18:19], v[2:3]
	v_mov_b64_e32 v[16:17], v[0:1]
	v_and_b32_e32 v200, 15, v192
	v_lshrrev_b32_e32 v201, 4, v192
	v_mul_u32_u24_e32 v179, 0x110, v201
	v_lshrrev_b32_e32 v202, 1, v200
	v_lshl_add_u32 v179, v202, 5, v179
	v_and_b32_e32 v202, 1, v200
	v_lshl_add_u32 v179, v202, 3, v179
	v_add_u32_e32 v179, 0x6800, v179
	v_add_u32_e32 v180, 0x2200, v179
	v_add_u32_e32 v186, 0xac00, v179
	v_add_u32_e32 v187, 0xac00, v180
	v_and_b32_e32 v200, 31, v192
	v_bfe_u32 v201, v192, 5, 1
	v_mul_u32_u24_e32 v191, 0x110, v200
	v_lshl_add_u32 v191, v201, 4, v191
	v_add_u32_e32 v191, 0x6800, v191
	s_waitcnt vmcnt(9)
; DI f32x16 zero16() { f32x16 z; for (int i = 0; i < 16; ++i) z[i] = 0.f; return z; }
; DI void phase_attn(const Params& p, int hf, bool skipctx, char* smem, int& rot) {
;     ...
;     f32x16 o[2]; o[0] = zero16(); o[1] = zero16();
;     float m_run = -1e30f, l_run = 0.f;
;     uint4 ak0, ak1, ak2, av0, av1, bk0, bk1, bk2, bv0, bv1;
;     const int kr0 = tid / 12, kc0 = tid - kr0 * 12, kr1 = (tid + 512) / 12, kc1 = (tid + 512) - kr1 * 12, kr2 = (tid + 1024) / 12, kc2 = (tid + 1024) - kr2 * 12;
;     const int vr0 = tid >> 4, vr1 = (tid + 512) >> 4, vc = tid & 15;
;     ...
;     ATT_WRITE(ak0, ak1, ak2, av0, av1, 0);
;     __syncthreads();
	ds_write_b128 v176, v[76:79]
	s_waitcnt vmcnt(8)
	ds_write_b128 v177, v[80:83]
	s_waitcnt vmcnt(7)
	ds_write_b128 v178, v[84:87]
	s_waitcnt vmcnt(6)
	ds_write_b64 v179, v[92:93] offset:0
	ds_write_b64 v179, v[94:95] offset:16
	s_waitcnt vmcnt(5)
	ds_write_b64 v179, v[104:105] offset:8704
	ds_write_b64 v179, v[106:107] offset:8720
	s_waitcnt lgkmcnt(0)
	s_barrier
	v_mov_b32_e32 v194, v176
	v_mov_b32_e32 v204, v177
	v_mov_b32_e32 v206, v178
	v_mov_b32_e32 v208, v179
	v_mov_b32_e32 v210, v190
	v_mov_b32_e32 v211, v191
	v_mov_b32_e32 v220, 0xf149f2ca
	v_mov_b32_e32 v176, 0
	v_mov_b32_e32 v177, 0
	v_mov_b32_e32 v178, 0
	v_mov_b32_e32 v179, 0
	v_mov_b32_e32 v180, 0
	v_mov_b32_e32 v181, 0
	v_mov_b32_e32 v182, 0
	v_mov_b32_e32 v183, 0
	v_mov_b32_e32 v184, 0
	v_mov_b32_e32 v185, 0
	v_mov_b32_e32 v186, 0
	v_mov_b32_e32 v187, 0
	v_mov_b32_e32 v188, 0
	v_mov_b32_e32 v189, 0
	v_mov_b32_e32 v190, 0
	v_mov_b32_e32 v191, 0
	v_add_u32_e32 v170, 0x18b28000, v170
	v_add_u32_e32 v172, 0x18b28000, v172
	v_add_u32_e32 v174, 0x18b28000, v174
	v_mov_b32_e32 v167, 0xbf800000
	s_mov_b32 s101, 0

; DI void phase_attn(const Params& p, int hf, bool skipctx, char* smem, int& rot) {
;     ...
;       const char* sk = smem + buf * STG + half * 64 * KROW; const char* sv = smem + buf * STG + KB_ + half * 128;
;       f32x16 st[2]; st[0] = zero16(); st[1] = zero16();
;       {
;         bf16x8 kf[2][6];
; #pragma unroll
;         for (int kb = 0; kb < 2; ++kb)
; #pragma unroll
;           for (int ks = 0; ks < 6; ++ks) kf[kb][ks] = *(const bf16x8*)(sk + (kb * 32 + r) * KROW + (ks * 16 + h * 8) * 2);
;         __builtin_amdgcn_sched_barrier(0);
; #pragma unroll
;         for (int ks = 0; ks < 6; ++ks)
; #pragma unroll
;           for (int kb = 0; kb < 2; ++kb) st[kb] = MFMA(kf[kb][ks], qf[ks], st[kb]);
;         __builtin_amdgcn_sched_barrier(0);
;       }
;       bf16x8 vf[2][2][2];
; #pragma unroll
;       for (int kb = 0; kb < 2; ++kb)
; #pragma unroll
;         for (int s2 = 0; s2 < 2; ++s2)
; #pragma unroll
;           for (int dvb = 0; dvb < 2; ++dvb) {
;             const char* vp = sv + (dvb * 32 + r) * VROW + (kb * 32 + 16 * s2 + 4 * h) * 2;
;             const s16x4 lo = *(const s16x4*)vp, hi = *(const s16x4*)(vp + 16);
;             vf[kb][s2][dvb] = __builtin_shufflevector(lo, hi, 0, 1, 2, 3, 4, 5, 6, 7);
;           }
;       float mx = st[0][0];
; #pragma unroll
;       for (int i = 0; i < 16; ++i) { mx = fmaxf(mx, st[0][i]); mx = fmaxf(mx, st[1][i]); }
;       if (__any(mx > m_run + 8.f)) {
;         mx = fmaxf(mx, __shfl_xor(mx, 32));
;         const float m_new = fmaxf(m_run, mx);
;         const float alpha = fexp2(m_run - m_new);
;         m_run = m_new;
;         l_run *= alpha;
; #pragma unroll
;         for (int i = 0; i < 16; ++i) { o[0][i] *= alpha; o[1][i] *= alpha; }
;       }
;       float ps = 0.f;
; #pragma unroll
;       for (int kb = 0; kb < 2; ++kb)
; #pragma unroll
;         for (int i = 0; i < 16; ++i) { const float e = fexp2(st[kb][i] - m_run); st[kb][i] = e; ps += e; }
;       l_run += ps;
; #pragma unroll
;       for (int kb = 0; kb < 2; ++kb)
; #pragma unroll
;         for (int s2 = 0; s2 < 2; ++s2) {
;           const bf16x8 pb = pack8(st[kb][8 * s2 + 0], st[kb][8 * s2 + 1], st[kb][8 * s2 + 2], st[kb][8 * s2 + 3], st[kb][8 * s2 + 4], st[kb][8 * s2 + 5], st[kb][8 * s2 + 6], st[kb][8 * s2 + 7]);
; #pragma unroll
;           for (int dvb = 0; dvb < 2; ++dvb) o[dvb] = MFMA(vf[kb][s2][dvb], pb, o[dvb]);
;         }
.LBB0_797:
	s_cmp_eq_u32 s101, 0
	s_cbranch_scc1 .Lsc0_fb0e
	s_waitcnt lgkmcnt(11)
	v_mfma_f32_32x32x16_bf16 v[48:63], v[32:35], v[64:67], v[176:191]
	s_waitcnt lgkmcnt(5)
	v_mfma_f32_32x32x16_bf16 v[32:47], v[36:39], v[64:67], v[176:191]
	v_mfma_f32_32x32x16_bf16 v[48:63], v[128:131], v[68:71], v[48:63]
	s_waitcnt lgkmcnt(4)
	v_mfma_f32_32x32x16_bf16 v[32:47], v[148:151], v[68:71], v[32:47]
	v_mfma_f32_32x32x16_bf16 v[48:63], v[132:135], v[72:75], v[48:63]
	s_waitcnt lgkmcnt(3)
	v_mfma_f32_32x32x16_bf16 v[32:47], v[152:155], v[72:75], v[32:47]
	v_mfma_f32_32x32x16_bf16 v[48:63], v[136:139], v[88:91], v[48:63]
	s_waitcnt lgkmcnt(2)
	v_mfma_f32_32x32x16_bf16 v[32:47], v[156:159], v[88:91], v[32:47]
	v_mfma_f32_32x32x16_bf16 v[48:63], v[140:143], v[96:99], v[48:63]
	s_waitcnt lgkmcnt(1)
	v_mfma_f32_32x32x16_bf16 v[32:47], v[214:217], v[96:99], v[32:47]
	v_mfma_f32_32x32x16_bf16 v[48:63], v[144:147], v[100:103], v[48:63]
	s_waitcnt lgkmcnt(0)
	v_mfma_f32_32x32x16_bf16 v[32:47], v[234:237], v[100:103], v[32:47]
	s_nop 3
	ds_read_b128 v[156:159], v211 offset:0
	ds_read_b128 v[148:151], v211 offset:32
	ds_read_b128 v[152:155], v211 offset:8704
	ds_read_b128 v[144:147], v211 offset:8736
	ds_read_b128 v[140:143], v211 offset:64
	ds_read_b128 v[136:139], v211 offset:8768
	ds_read_b128 v[132:135], v211 offset:96
	ds_read_b128 v[128:131], v211 offset:8800
	v_exp_f32_e32 v48, v48
	v_exp_f32_e32 v49, v49
	v_exp_f32_e32 v50, v50
	v_exp_f32_e32 v51, v51
	v_exp_f32_e32 v52, v52
	v_exp_f32_e32 v53, v53
	v_exp_f32_e32 v54, v54
	v_exp_f32_e32 v55, v55
	v_exp_f32_e32 v56, v56
	v_exp_f32_e32 v57, v57
	v_exp_f32_e32 v58, v58
	v_exp_f32_e32 v59, v59
	v_exp_f32_e32 v60, v60
	v_exp_f32_e32 v61, v61
	v_exp_f32_e32 v62, v62
	v_exp_f32_e32 v63, v63
	v_exp_f32_e32 v32, v32
	v_exp_f32_e32 v33, v33
	v_exp_f32_e32 v34, v34
	v_exp_f32_e32 v35, v35
	v_exp_f32_e32 v36, v36
	v_exp_f32_e32 v37, v37
	v_exp_f32_e32 v38, v38
	v_exp_f32_e32 v39, v39
	v_exp_f32_e32 v40, v40
	v_exp_f32_e32 v41, v41
	v_exp_f32_e32 v42, v42
	v_exp_f32_e32 v43, v43
	v_exp_f32_e32 v44, v44
	v_exp_f32_e32 v45, v45
	v_exp_f32_e32 v46, v46
	v_exp_f32_e32 v47, v47
	v_add_f32_e32 v195, v48, v49
	v_add_f32_e32 v195, v195, v50
	v_add_f32_e32 v195, v195, v51
	v_add_f32_e32 v195, v195, v52
	v_add_f32_e32 v195, v195, v53
	v_add_f32_e32 v195, v195, v54
	v_add_f32_e32 v195, v195, v55
	v_add_f32_e32 v195, v195, v56
	v_add_f32_e32 v195, v195, v57
	v_add_f32_e32 v195, v195, v58
	v_add_f32_e32 v195, v195, v59
	v_add_f32_e32 v195, v195, v60
	v_add_f32_e32 v195, v195, v61
	v_add_f32_e32 v195, v195, v62
	v_add_f32_e32 v195, v195, v63
	v_add_f32_e32 v195, v195, v32
	v_add_f32_e32 v195, v195, v33
	v_add_f32_e32 v195, v195, v34
	v_add_f32_e32 v195, v195, v35
	v_add_f32_e32 v195, v195, v36
	v_add_f32_e32 v195, v195, v37
	v_add_f32_e32 v195, v195, v38
	v_add_f32_e32 v195, v195, v39
	v_add_f32_e32 v195, v195, v40
	v_add_f32_e32 v195, v195, v41
	v_add_f32_e32 v195, v195, v42
	v_add_f32_e32 v195, v195, v43
	v_add_f32_e32 v195, v195, v44
	v_add_f32_e32 v195, v195, v45
	v_add_f32_e32 v195, v195, v46
	v_add_f32_e32 v195, v195, v47
	v_cmp_nle_f32_e32 vcc, v195, v167
	s_cbranch_vccnz .Lsc0_fb0
	v_add_f32_e32 v213, v213, v195
	v_cvt_pk_bf16_f32 v48, v48, v49
	v_cvt_pk_bf16_f32 v49, v50, v51
	v_cvt_pk_bf16_f32 v50, v52, v53
	v_cvt_pk_bf16_f32 v51, v54, v55
	v_cvt_pk_bf16_f32 v52, v56, v57
	v_cvt_pk_bf16_f32 v53, v58, v59
	v_cvt_pk_bf16_f32 v54, v60, v61
	v_cvt_pk_bf16_f32 v55, v62, v63
	v_cvt_pk_bf16_f32 v56, v32, v33
	v_cvt_pk_bf16_f32 v57, v34, v35
	v_cvt_pk_bf16_f32 v58, v36, v37
	v_cvt_pk_bf16_f32 v59, v38, v39
	v_cvt_pk_bf16_f32 v60, v40, v41
	v_cvt_pk_bf16_f32 v61, v42, v43
	v_cvt_pk_bf16_f32 v62, v44, v45
	v_cvt_pk_bf16_f32 v63, v46, v47
	s_waitcnt lgkmcnt(7)
	v_mfma_f32_32x32x16_bf16 v[16:31], v[156:159], v[48:51], v[16:31]
	s_waitcnt lgkmcnt(5)
	v_mfma_f32_32x32x16_bf16 v[0:15], v[152:155], v[48:51], v[0:15]
	s_nop 0
	v_mfma_f32_32x32x16_bf16 v[16:31], v[148:151], v[52:55], v[16:31]
	s_waitcnt lgkmcnt(4)
	v_mfma_f32_32x32x16_bf16 v[0:15], v[144:147], v[52:55], v[0:15]
	s_waitcnt lgkmcnt(3)
	v_mfma_f32_32x32x16_bf16 v[16:31], v[140:143], v[56:59], v[16:31]
	s_waitcnt lgkmcnt(2)
	v_mfma_f32_32x32x16_bf16 v[0:15], v[136:139], v[56:59], v[0:15]
	s_waitcnt lgkmcnt(1)
	s_nop 0
	v_mfma_f32_32x32x16_bf16 v[16:31], v[132:135], v[60:63], v[16:31]
	ds_read_b128 v[36:39], v210 offset:13312
	ds_read_b128 v[132:135], v210 offset:13344
	ds_read_b128 v[136:139], v210 offset:13376
	ds_read_b128 v[140:143], v210 offset:13408
	ds_read_b128 v[144:147], v210 offset:13440
	ds_read_b128 v[148:151], v210 offset:13472
	ds_read_b128 v[40:43], v210 offset:19968
	ds_read_b128 v[152:155], v210 offset:20000
	ds_read_b128 v[156:159], v210 offset:20032
	ds_read_b128 v[234:237], v210 offset:20064
	ds_read_b128 v[238:241], v210 offset:20096
	ds_read_b128 v[242:245], v210 offset:20128
	s_waitcnt lgkmcnt(12)
	v_mfma_f32_32x32x16_bf16 v[0:15], v[128:131], v[60:63], v[0:15]

; #define MFMA(a, b, c) __builtin_amdgcn_mfma_f32_32x32x16_bf16((a), (b), (c), 0, 0, 0)
; DI float fexp2(float x) { return __builtin_amdgcn_exp2f(x); }
; DI f32x16 zero16() { f32x16 z; for (int i = 0; i < 16; ++i) z[i] = 0.f; return z; }
; DI void phase_attn(const Params& p, int hf, bool skipctx, char* smem, int& rot) {
;     ...
;       const char* sk = smem + buf * STG + half * 64 * KROW; const char* sv = smem + buf * STG + KB_ + half * 128;
;       f32x16 st[2]; st[0] = zero16(); st[1] = zero16();
;       {
;         bf16x8 kf[2][6];
; #pragma unroll
;         for (int kb = 0; kb < 2; ++kb)
; #pragma unroll
;           for (int ks = 0; ks < 6; ++ks) kf[kb][ks] = *(const bf16x8*)(sk + (kb * 32 + r) * KROW + (ks * 16 + h * 8) * 2);
;         __builtin_amdgcn_sched_barrier(0);
; #pragma unroll
;         for (int ks = 0; ks < 6; ++ks)
; #pragma unroll
;           for (int kb = 0; kb < 2; ++kb) st[kb] = MFMA(kf[kb][ks], qf[ks], st[kb]);
;         __builtin_amdgcn_sched_barrier(0);
;       }
;       bf16x8 vf[2][2][2];
; #pragma unroll
;       for (int kb = 0; kb < 2; ++kb)
; #pragma unroll
;         for (int s2 = 0; s2 < 2; ++s2)
; #pragma unroll
;           for (int dvb = 0; dvb < 2; ++dvb) {
;             const char* vp = sv + (dvb * 32 + r) * VROW + (kb * 32 + 16 * s2 + 4 * h) * 2;
;             const s16x4 lo = *(const s16x4*)vp, hi = *(const s16x4*)(vp + 16);
;             vf[kb][s2][dvb] = __builtin_shufflevector(lo, hi, 0, 1, 2, 3, 4, 5, 6, 7);
;           }
;       float mx = st[0][0];
; #pragma unroll
;       for (int i = 0; i < 16; ++i) { mx = fmaxf(mx, st[0][i]); mx = fmaxf(mx, st[1][i]); }
;       if (__any(mx > m_run + 8.f)) {
;         mx = fmaxf(mx, __shfl_xor(mx, 32));
;         const float m_new = fmaxf(m_run, mx);
;         const float alpha = fexp2(m_run - m_new);
;         m_run = m_new;
;         l_run *= alpha;
; #pragma unroll
;         for (int i = 0; i < 16; ++i) { o[0][i] *= alpha; o[1][i] *= alpha; }
;       }
.Lsc0_fb0e:
	s_waitcnt lgkmcnt(11)
	v_mfma_f32_32x32x16_bf16 v[48:63], v[32:35], v[64:67], v[176:191]
	s_waitcnt lgkmcnt(5)
	v_mfma_f32_32x32x16_bf16 v[32:47], v[36:39], v[64:67], v[176:191]
	v_mfma_f32_32x32x16_bf16 v[48:63], v[128:131], v[68:71], v[48:63]
	s_waitcnt lgkmcnt(4)
	v_mfma_f32_32x32x16_bf16 v[32:47], v[148:151], v[68:71], v[32:47]
	v_mfma_f32_32x32x16_bf16 v[48:63], v[132:135], v[72:75], v[48:63]
	s_waitcnt lgkmcnt(3)
	v_mfma_f32_32x32x16_bf16 v[32:47], v[152:155], v[72:75], v[32:47]
	v_mfma_f32_32x32x16_bf16 v[48:63], v[136:139], v[88:91], v[48:63]
	s_waitcnt lgkmcnt(2)
	v_mfma_f32_32x32x16_bf16 v[32:47], v[156:159], v[88:91], v[32:47]
	v_mfma_f32_32x32x16_bf16 v[48:63], v[140:143], v[96:99], v[48:63]
	s_waitcnt lgkmcnt(1)
	v_mfma_f32_32x32x16_bf16 v[32:47], v[214:217], v[96:99], v[32:47]
	v_mfma_f32_32x32x16_bf16 v[48:63], v[144:147], v[100:103], v[48:63]
	s_waitcnt lgkmcnt(0)
	v_mfma_f32_32x32x16_bf16 v[32:47], v[234:237], v[100:103], v[32:47]
	s_nop 3
	ds_read_b128 v[156:159], v211 offset:0
	ds_read_b128 v[148:151], v211 offset:32
	ds_read_b128 v[152:155], v211 offset:8704
	ds_read_b128 v[144:147], v211 offset:8736
	ds_read_b128 v[140:143], v211 offset:64
	ds_read_b128 v[136:139], v211 offset:8768
	ds_read_b128 v[132:135], v211 offset:96
	ds_read_b128 v[128:131], v211 offset:8800
	v_max3_f32 v195, v32, v48, v49
	v_max_f32_e32 v195, v195, v33
	v_max3_f32 v195, v195, v50, v34
	v_max3_f32 v195, v195, v51, v35
	v_max3_f32 v195, v195, v52, v36
	v_max3_f32 v195, v195, v53, v37
	v_max3_f32 v195, v195, v54, v38
	v_max3_f32 v195, v195, v55, v39
	v_max3_f32 v195, v195, v56, v40
	v_max3_f32 v195, v195, v57, v41
	v_max3_f32 v195, v195, v58, v42
	v_max3_f32 v195, v195, v59, v43
	v_max3_f32 v195, v195, v60, v44
	v_max3_f32 v195, v195, v61, v45
	v_max3_f32 v195, v195, v62, v46
	v_max3_f32 v217, v195, v63, v47
	v_cmp_gt_f32_e32 vcc, v217, v220
	s_cbranch_vccz .Lsc0_c0_LBB0_799
	v_sub_f32_e32 v217, v217, v176
	v_cmp_lt_i32_e32 vcc, v224, v207
	s_nop 1
	v_cndmask_b32_e32 v195, v205, v224, vcc
	v_lshlrev_b32_e32 v195, 2, v195
	ds_bpermute_b32 v195, v195, v217
	s_waitcnt lgkmcnt(0)
	v_max3_f32 v195, v212, v217, v195
	v_sub_f32_e32 v200, v212, v195
	v_exp_f32_e32 v200, v200
	v_mov_b32_e32 v212, v195
	v_mul_f32_e32 v213, v213, v200
	v_pk_mul_f32 v[30:31], v[30:31], v[200:201] op_sel_hi:[1,0]
	v_pk_mul_f32 v[28:29], v[28:29], v[200:201] op_sel_hi:[1,0]
	v_pk_mul_f32 v[26:27], v[26:27], v[200:201] op_sel_hi:[1,0]
	v_pk_mul_f32 v[24:25], v[24:25], v[200:201] op_sel_hi:[1,0]
	v_pk_mul_f32 v[22:23], v[22:23], v[200:201] op_sel_hi:[1,0]
	v_pk_mul_f32 v[20:21], v[20:21], v[200:201] op_sel_hi:[1,0]
	v_pk_mul_f32 v[18:19], v[18:19], v[200:201] op_sel_hi:[1,0]
	v_pk_mul_f32 v[16:17], v[16:17], v[200:201] op_sel_hi:[1,0]
	v_pk_mul_f32 v[14:15], v[14:15], v[200:201] op_sel_hi:[1,0]
	v_pk_mul_f32 v[12:13], v[12:13], v[200:201] op_sel_hi:[1,0]
	v_pk_mul_f32 v[10:11], v[10:11], v[200:201] op_sel_hi:[1,0]
	v_pk_mul_f32 v[8:9], v[8:9], v[200:201] op_sel_hi:[1,0]
	v_pk_mul_f32 v[6:7], v[6:7], v[200:201] op_sel_hi:[1,0]
	v_pk_mul_f32 v[4:5], v[4:5], v[200:201] op_sel_hi:[1,0]
	v_pk_mul_f32 v[2:3], v[2:3], v[200:201] op_sel_hi:[1,0]
	v_pk_mul_f32 v[0:1], v[0:1], v[200:201] op_sel_hi:[1,0]
	v_add_f32_e32 v202, v195, v176
	v_sub_f32_e32 v32, v32, v202
	v_sub_f32_e32 v33, v33, v202
	v_sub_f32_e32 v34, v34, v202
	v_sub_f32_e32 v35, v35, v202
	v_sub_f32_e32 v36, v36, v202
	v_sub_f32_e32 v37, v37, v202
	v_sub_f32_e32 v38, v38, v202
	v_sub_f32_e32 v39, v39, v202
	v_sub_f32_e32 v40, v40, v202
	v_sub_f32_e32 v41, v41, v202
	v_sub_f32_e32 v42, v42, v202
	v_sub_f32_e32 v43, v43, v202
	v_sub_f32_e32 v44, v44, v202
	v_sub_f32_e32 v45, v45, v202
	v_sub_f32_e32 v46, v46, v202
	v_sub_f32_e32 v47, v47, v202
	v_sub_f32_e32 v48, v48, v202
	v_sub_f32_e32 v49, v49, v202
	v_sub_f32_e32 v50, v50, v202
	v_sub_f32_e32 v51, v51, v202
	v_sub_f32_e32 v52, v52, v202
	v_sub_f32_e32 v53, v53, v202
	v_sub_f32_e32 v54, v54, v202
	v_sub_f32_e32 v55, v55, v202
	v_sub_f32_e32 v56, v56, v202
	v_sub_f32_e32 v57, v57, v202
	v_sub_f32_e32 v58, v58, v202
	v_sub_f32_e32 v59, v59, v202
	v_sub_f32_e32 v60, v60, v202
	v_sub_f32_e32 v61, v61, v202
	v_sub_f32_e32 v62, v62, v202
	v_sub_f32_e32 v63, v63, v202
	v_sub_f32_e32 v176, 0, v195
	v_sub_f32_e32 v177, 0, v195
	v_sub_f32_e32 v178, 0, v195
	v_sub_f32_e32 v179, 0, v195
	v_sub_f32_e32 v180, 0, v195
	v_sub_f32_e32 v181, 0, v195
	v_sub_f32_e32 v182, 0, v195
	v_sub_f32_e32 v183, 0, v195
	v_sub_f32_e32 v184, 0, v195
	v_sub_f32_e32 v185, 0, v195
	v_sub_f32_e32 v186, 0, v195
	v_sub_f32_e32 v187, 0, v195
	v_sub_f32_e32 v188, 0, v195
	v_sub_f32_e32 v189, 0, v195
	v_sub_f32_e32 v190, 0, v195
	v_sub_f32_e32 v191, 0, v195
	v_mov_b32_e32 v220, 0x41000000
	v_mov_b32_e32 v167, 0x43800000
	s_mov_b32 s101, 1

; #define MFMA(a, b, c) __builtin_amdgcn_mfma_f32_32x32x16_bf16((a), (b), (c), 0, 0, 0)
; DI float fexp2(float x) { return __builtin_amdgcn_exp2f(x); }
; DI f32x16 zero16() { f32x16 z; for (int i = 0; i < 16; ++i) z[i] = 0.f; return z; }
; DI void phase_attn(const Params& p, int hf, bool skipctx, char* smem, int& rot) {
;     ...
;       const char* sk = smem + buf * STG + half * 64 * KROW; const char* sv = smem + buf * STG + KB_ + half * 128;
;       f32x16 st[2]; st[0] = zero16(); st[1] = zero16();
;       {
;         bf16x8 kf[2][6];
; #pragma unroll
;         for (int kb = 0; kb < 2; ++kb)
; #pragma unroll
;           for (int ks = 0; ks < 6; ++ks) kf[kb][ks] = *(const bf16x8*)(sk + (kb * 32 + r) * KROW + (ks * 16 + h * 8) * 2);
;         __builtin_amdgcn_sched_barrier(0);
; #pragma unroll
;         for (int ks = 0; ks < 6; ++ks)
; #pragma unroll
;           for (int kb = 0; kb < 2; ++kb) st[kb] = MFMA(kf[kb][ks], qf[ks], st[kb]);
;         __builtin_amdgcn_sched_barrier(0);
;       }
;       bf16x8 vf[2][2][2];
; #pragma unroll
;       for (int kb = 0; kb < 2; ++kb)
; #pragma unroll
;         for (int s2 = 0; s2 < 2; ++s2)
; #pragma unroll
;           for (int dvb = 0; dvb < 2; ++dvb) {
;             const char* vp = sv + (dvb * 32 + r) * VROW + (kb * 32 + 16 * s2 + 4 * h) * 2;
;             const s16x4 lo = *(const s16x4*)vp, hi = *(const s16x4*)(vp + 16);
;             vf[kb][s2][dvb] = __builtin_shufflevector(lo, hi, 0, 1, 2, 3, 4, 5, 6, 7);
;           }
;       float mx = st[0][0];
; #pragma unroll
;       for (int i = 0; i < 16; ++i) { mx = fmaxf(mx, st[0][i]); mx = fmaxf(mx, st[1][i]); }
;       if (__any(mx > m_run + 8.f)) {
;         mx = fmaxf(mx, __shfl_xor(mx, 32));
;         const float m_new = fmaxf(m_run, mx);
;         const float alpha = fexp2(m_run - m_new);
;         m_run = m_new;
;         l_run *= alpha;
; #pragma unroll
;         for (int i = 0; i < 16; ++i) { o[0][i] *= alpha; o[1][i] *= alpha; }
;       }
.Lsc0_fb1:
	ds_read_b128 v[36:39], v210 offset:13312
	ds_read_b128 v[132:135], v210 offset:13344
	ds_read_b128 v[136:139], v210 offset:13376
	ds_read_b128 v[140:143], v210 offset:13408
	ds_read_b128 v[144:147], v210 offset:13440
	ds_read_b128 v[148:151], v210 offset:13472
	ds_read_b128 v[40:43], v210 offset:19968
	ds_read_b128 v[152:155], v210 offset:20000
	ds_read_b128 v[156:159], v210 offset:20032
	ds_read_b128 v[234:237], v210 offset:20064
	ds_read_b128 v[238:241], v210 offset:20096
	ds_read_b128 v[242:245], v210 offset:20128
	s_waitcnt lgkmcnt(0)
	s_waitcnt lgkmcnt(11)
	v_mfma_f32_32x32x16_bf16 v[48:63], v[36:39], v[64:67], v[176:191]
	s_waitcnt lgkmcnt(5)
	v_mfma_f32_32x32x16_bf16 v[32:47], v[40:43], v[64:67], v[176:191]
	v_mfma_f32_32x32x16_bf16 v[48:63], v[132:135], v[68:71], v[48:63]
	s_waitcnt lgkmcnt(4)
	v_mfma_f32_32x32x16_bf16 v[32:47], v[152:155], v[68:71], v[32:47]
	v_mfma_f32_32x32x16_bf16 v[48:63], v[136:139], v[72:75], v[48:63]
	s_waitcnt lgkmcnt(3)
	v_mfma_f32_32x32x16_bf16 v[32:47], v[156:159], v[72:75], v[32:47]
	v_mfma_f32_32x32x16_bf16 v[48:63], v[140:143], v[88:91], v[48:63]
	s_waitcnt lgkmcnt(2)
	v_mfma_f32_32x32x16_bf16 v[32:47], v[234:237], v[88:91], v[32:47]
	v_mfma_f32_32x32x16_bf16 v[48:63], v[144:147], v[96:99], v[48:63]
	s_waitcnt lgkmcnt(1)
	v_mfma_f32_32x32x16_bf16 v[32:47], v[238:241], v[96:99], v[32:47]
	v_mfma_f32_32x32x16_bf16 v[48:63], v[148:151], v[100:103], v[48:63]
	s_waitcnt lgkmcnt(0)
	v_mfma_f32_32x32x16_bf16 v[32:47], v[242:245], v[100:103], v[32:47]
	s_nop 3
	ds_read_b128 v[156:159], v211 offset:128
	ds_read_b128 v[148:151], v211 offset:160
	ds_read_b128 v[152:155], v211 offset:8832
	ds_read_b128 v[144:147], v211 offset:8864
	ds_read_b128 v[140:143], v211 offset:192
	ds_read_b128 v[136:139], v211 offset:8896
	ds_read_b128 v[128:131], v211 offset:224
	ds_read_b128 v[132:135], v211 offset:8928
	v_max3_f32 v195, v32, v48, v49
	v_max_f32_e32 v195, v195, v33
	v_max3_f32 v195, v195, v50, v34
	v_max3_f32 v195, v195, v51, v35
	v_max3_f32 v195, v195, v52, v36
	v_max3_f32 v195, v195, v53, v37
	v_max3_f32 v195, v195, v54, v38
	v_max3_f32 v195, v195, v55, v39
	v_max3_f32 v195, v195, v56, v40
	v_max3_f32 v195, v195, v57, v41
	v_max3_f32 v195, v195, v58, v42
	v_max3_f32 v195, v195, v59, v43
	v_max3_f32 v195, v195, v60, v44
	v_max3_f32 v195, v195, v61, v45
	v_max3_f32 v195, v195, v62, v46
	v_max3_f32 v214, v195, v63, v47
	v_cmp_gt_f32_e32 vcc, v214, v220
	s_cbranch_vccz .Lsc0_c1_LBB0_801
	v_sub_f32_e32 v214, v214, v176
	v_cmp_lt_i32_e32 vcc, v224, v207
	s_nop 1
	v_cndmask_b32_e32 v195, v205, v224, vcc
	v_lshlrev_b32_e32 v195, 2, v195
	ds_bpermute_b32 v195, v195, v214
	s_waitcnt lgkmcnt(0)
	v_max3_f32 v195, v212, v214, v195
	v_sub_f32_e32 v200, v212, v195
	v_exp_f32_e32 v200, v200
	v_mov_b32_e32 v212, v195
	v_mul_f32_e32 v213, v213, v200
	v_pk_mul_f32 v[30:31], v[30:31], v[200:201] op_sel_hi:[1,0]
	v_pk_mul_f32 v[28:29], v[28:29], v[200:201] op_sel_hi:[1,0]
	v_pk_mul_f32 v[26:27], v[26:27], v[200:201] op_sel_hi:[1,0]
	v_pk_mul_f32 v[24:25], v[24:25], v[200:201] op_sel_hi:[1,0]
	v_pk_mul_f32 v[22:23], v[22:23], v[200:201] op_sel_hi:[1,0]
	v_pk_mul_f32 v[20:21], v[20:21], v[200:201] op_sel_hi:[1,0]
	v_pk_mul_f32 v[18:19], v[18:19], v[200:201] op_sel_hi:[1,0]
	v_pk_mul_f32 v[16:17], v[16:17], v[200:201] op_sel_hi:[1,0]
	v_pk_mul_f32 v[14:15], v[14:15], v[200:201] op_sel_hi:[1,0]
	v_pk_mul_f32 v[12:13], v[12:13], v[200:201] op_sel_hi:[1,0]
	v_pk_mul_f32 v[10:11], v[10:11], v[200:201] op_sel_hi:[1,0]
	v_pk_mul_f32 v[8:9], v[8:9], v[200:201] op_sel_hi:[1,0]
	v_pk_mul_f32 v[6:7], v[6:7], v[200:201] op_sel_hi:[1,0]
	v_pk_mul_f32 v[4:5], v[4:5], v[200:201] op_sel_hi:[1,0]
	v_pk_mul_f32 v[2:3], v[2:3], v[200:201] op_sel_hi:[1,0]
	v_pk_mul_f32 v[0:1], v[0:1], v[200:201] op_sel_hi:[1,0]
	v_add_f32_e32 v202, v195, v176
	v_sub_f32_e32 v32, v32, v202
	v_sub_f32_e32 v33, v33, v202
	v_sub_f32_e32 v34, v34, v202
	v_sub_f32_e32 v35, v35, v202
	v_sub_f32_e32 v36, v36, v202
	v_sub_f32_e32 v37, v37, v202
	v_sub_f32_e32 v38, v38, v202
	v_sub_f32_e32 v39, v39, v202
	v_sub_f32_e32 v40, v40, v202
	v_sub_f32_e32 v41, v41, v202
	v_sub_f32_e32 v42, v42, v202
	v_sub_f32_e32 v43, v43, v202
	v_sub_f32_e32 v44, v44, v202
	v_sub_f32_e32 v45, v45, v202
	v_sub_f32_e32 v46, v46, v202
	v_sub_f32_e32 v47, v47, v202
	v_sub_f32_e32 v48, v48, v202
	v_sub_f32_e32 v49, v49, v202
	v_sub_f32_e32 v50, v50, v202
	v_sub_f32_e32 v51, v51, v202
	v_sub_f32_e32 v52, v52, v202
	v_sub_f32_e32 v53, v53, v202
	v_sub_f32_e32 v54, v54, v202
	v_sub_f32_e32 v55, v55, v202
	v_sub_f32_e32 v56, v56, v202
	v_sub_f32_e32 v57, v57, v202
	v_sub_f32_e32 v58, v58, v202
	v_sub_f32_e32 v59, v59, v202
	v_sub_f32_e32 v60, v60, v202
	v_sub_f32_e32 v61, v61, v202
	v_sub_f32_e32 v62, v62, v202
	v_sub_f32_e32 v63, v63, v202
	v_sub_f32_e32 v176, 0, v195
	v_sub_f32_e32 v177, 0, v195
	v_sub_f32_e32 v178, 0, v195
	v_sub_f32_e32 v179, 0, v195
	v_sub_f32_e32 v180, 0, v195
	v_sub_f32_e32 v181, 0, v195
	v_sub_f32_e32 v182, 0, v195
	v_sub_f32_e32 v183, 0, v195
	v_sub_f32_e32 v184, 0, v195
	v_sub_f32_e32 v185, 0, v195
	v_sub_f32_e32 v186, 0, v195
	v_sub_f32_e32 v187, 0, v195
	v_sub_f32_e32 v188, 0, v195
	v_sub_f32_e32 v189, 0, v195
	v_sub_f32_e32 v190, 0, v195
	v_sub_f32_e32 v191, 0, v195
	v_mov_b32_e32 v220, 0x41000000
	v_mov_b32_e32 v167, 0x43800000
	s_mov_b32 s101, 1

; #define MFMA(a, b, c) __builtin_amdgcn_mfma_f32_32x32x16_bf16((a), (b), (c), 0, 0, 0)
; DI float fexp2(float x) { return __builtin_amdgcn_exp2f(x); }
; DI f32x16 zero16() { f32x16 z; for (int i = 0; i < 16; ++i) z[i] = 0.f; return z; }
; DI void phase_attn(const Params& p, int hf, bool skipctx, char* smem, int& rot) {
;     ...
;       const char* sk = smem + buf * STG + half * 64 * KROW; const char* sv = smem + buf * STG + KB_ + half * 128;
;       f32x16 st[2]; st[0] = zero16(); st[1] = zero16();
;       {
;         bf16x8 kf[2][6];
; #pragma unroll
;         for (int kb = 0; kb < 2; ++kb)
; #pragma unroll
;           for (int ks = 0; ks < 6; ++ks) kf[kb][ks] = *(const bf16x8*)(sk + (kb * 32 + r) * KROW + (ks * 16 + h * 8) * 2);
;         __builtin_amdgcn_sched_barrier(0);
; #pragma unroll
;         for (int ks = 0; ks < 6; ++ks)
; #pragma unroll
;           for (int kb = 0; kb < 2; ++kb) st[kb] = MFMA(kf[kb][ks], qf[ks], st[kb]);
;         __builtin_amdgcn_sched_barrier(0);
;       }
;       bf16x8 vf[2][2][2];
; #pragma unroll
;       for (int kb = 0; kb < 2; ++kb)
; #pragma unroll
;         for (int s2 = 0; s2 < 2; ++s2)
; #pragma unroll
;           for (int dvb = 0; dvb < 2; ++dvb) {
;             const char* vp = sv + (dvb * 32 + r) * VROW + (kb * 32 + 16 * s2 + 4 * h) * 2;
;             const s16x4 lo = *(const s16x4*)vp, hi = *(const s16x4*)(vp + 16);
;             vf[kb][s2][dvb] = __builtin_shufflevector(lo, hi, 0, 1, 2, 3, 4, 5, 6, 7);
;           }
;       float mx = st[0][0];
; #pragma unroll
;       for (int i = 0; i < 16; ++i) { mx = fmaxf(mx, st[0][i]); mx = fmaxf(mx, st[1][i]); }
;       if (__any(mx > m_run + 8.f)) {
;         mx = fmaxf(mx, __shfl_xor(mx, 32));
;         const float m_new = fmaxf(m_run, mx);
;         const float alpha = fexp2(m_run - m_new);
;         m_run = m_new;
;         l_run *= alpha;
; #pragma unroll
;         for (int i = 0; i < 16; ++i) { o[0][i] *= alpha; o[1][i] *= alpha; }
;       }
.Lsc0_fb2:
	ds_read_b128 v[32:35], v210 offset:44032
	ds_read_b128 v[128:131], v210 offset:44064
	ds_read_b128 v[132:135], v210 offset:44096
	ds_read_b128 v[136:139], v210 offset:44128
	ds_read_b128 v[140:143], v210 offset:44160
	ds_read_b128 v[144:147], v210 offset:44192
	ds_read_b128 v[36:39], v210 offset:50688
	ds_read_b128 v[148:151], v210 offset:50720
	ds_read_b128 v[152:155], v210 offset:50752
	ds_read_b128 v[156:159], v210 offset:50784
	ds_read_b128 v[214:217], v210 offset:50816
	ds_read_b128 v[234:237], v210 offset:50848
	s_waitcnt lgkmcnt(0)
	s_waitcnt lgkmcnt(11)
	v_mfma_f32_32x32x16_bf16 v[48:63], v[32:35], v[64:67], v[176:191]
	s_waitcnt lgkmcnt(5)
	v_mfma_f32_32x32x16_bf16 v[32:47], v[36:39], v[64:67], v[176:191]
	v_mfma_f32_32x32x16_bf16 v[48:63], v[128:131], v[68:71], v[48:63]
	s_waitcnt lgkmcnt(4)
	v_mfma_f32_32x32x16_bf16 v[32:47], v[148:151], v[68:71], v[32:47]
	v_mfma_f32_32x32x16_bf16 v[48:63], v[132:135], v[72:75], v[48:63]
	s_waitcnt lgkmcnt(3)
	v_mfma_f32_32x32x16_bf16 v[32:47], v[152:155], v[72:75], v[32:47]
	v_mfma_f32_32x32x16_bf16 v[48:63], v[136:139], v[88:91], v[48:63]
	s_waitcnt lgkmcnt(2)
	v_mfma_f32_32x32x16_bf16 v[32:47], v[156:159], v[88:91], v[32:47]
	v_mfma_f32_32x32x16_bf16 v[48:63], v[140:143], v[96:99], v[48:63]
	s_waitcnt lgkmcnt(1)
	v_mfma_f32_32x32x16_bf16 v[32:47], v[214:217], v[96:99], v[32:47]
	v_mfma_f32_32x32x16_bf16 v[48:63], v[144:147], v[100:103], v[48:63]
	s_waitcnt lgkmcnt(0)
	v_mfma_f32_32x32x16_bf16 v[32:47], v[234:237], v[100:103], v[32:47]
	s_nop 3
	ds_read_b128 v[152:155], v211 offset:52736
	ds_read_b128 v[156:159], v211 offset:44032
	ds_read_b128 v[148:151], v211 offset:44064
	ds_read_b128 v[144:147], v211 offset:52768
	ds_read_b128 v[140:143], v211 offset:44096
	ds_read_b128 v[136:139], v211 offset:52800
	ds_read_b128 v[132:135], v211 offset:44128
	ds_read_b128 v[128:131], v211 offset:52832
	v_max3_f32 v195, v32, v48, v49
	v_max_f32_e32 v195, v195, v33
	v_max3_f32 v195, v195, v50, v34
	v_max3_f32 v195, v195, v51, v35
	v_max3_f32 v195, v195, v52, v36
	v_max3_f32 v195, v195, v53, v37
	v_max3_f32 v195, v195, v54, v38
	v_max3_f32 v195, v195, v55, v39
	v_max3_f32 v195, v195, v56, v40
	v_max3_f32 v195, v195, v57, v41
	v_max3_f32 v195, v195, v58, v42
	v_max3_f32 v195, v195, v59, v43
	v_max3_f32 v195, v195, v60, v44
	v_max3_f32 v195, v195, v61, v45
	v_max3_f32 v195, v195, v62, v46
	v_max3_f32 v215, v195, v63, v47
	v_cmp_gt_f32_e32 vcc, v215, v220
	s_cbranch_vccz .Lsc0_c2_LBB0_805
	v_sub_f32_e32 v215, v215, v176
	v_cmp_lt_i32_e32 vcc, v224, v207
	s_nop 1
	v_cndmask_b32_e32 v195, v205, v224, vcc
	v_lshlrev_b32_e32 v195, 2, v195
	ds_bpermute_b32 v195, v195, v215
	s_waitcnt lgkmcnt(0)
	v_max3_f32 v195, v212, v215, v195
	v_sub_f32_e32 v200, v212, v195
	v_exp_f32_e32 v200, v200
	v_mov_b32_e32 v212, v195
	v_mul_f32_e32 v213, v213, v200
	v_pk_mul_f32 v[30:31], v[30:31], v[200:201] op_sel_hi:[1,0]
	v_pk_mul_f32 v[28:29], v[28:29], v[200:201] op_sel_hi:[1,0]
	v_pk_mul_f32 v[26:27], v[26:27], v[200:201] op_sel_hi:[1,0]
	v_pk_mul_f32 v[24:25], v[24:25], v[200:201] op_sel_hi:[1,0]
	v_pk_mul_f32 v[22:23], v[22:23], v[200:201] op_sel_hi:[1,0]
	v_pk_mul_f32 v[20:21], v[20:21], v[200:201] op_sel_hi:[1,0]
	v_pk_mul_f32 v[18:19], v[18:19], v[200:201] op_sel_hi:[1,0]
	v_pk_mul_f32 v[16:17], v[16:17], v[200:201] op_sel_hi:[1,0]
	v_pk_mul_f32 v[14:15], v[14:15], v[200:201] op_sel_hi:[1,0]
	v_pk_mul_f32 v[12:13], v[12:13], v[200:201] op_sel_hi:[1,0]
	v_pk_mul_f32 v[10:11], v[10:11], v[200:201] op_sel_hi:[1,0]
	v_pk_mul_f32 v[8:9], v[8:9], v[200:201] op_sel_hi:[1,0]
	v_pk_mul_f32 v[6:7], v[6:7], v[200:201] op_sel_hi:[1,0]
	v_pk_mul_f32 v[4:5], v[4:5], v[200:201] op_sel_hi:[1,0]
	v_pk_mul_f32 v[2:3], v[2:3], v[200:201] op_sel_hi:[1,0]
	v_pk_mul_f32 v[0:1], v[0:1], v[200:201] op_sel_hi:[1,0]
	v_add_f32_e32 v202, v195, v176
	v_sub_f32_e32 v32, v32, v202
	v_sub_f32_e32 v33, v33, v202
	v_sub_f32_e32 v34, v34, v202
	v_sub_f32_e32 v35, v35, v202
	v_sub_f32_e32 v36, v36, v202
	v_sub_f32_e32 v37, v37, v202
	v_sub_f32_e32 v38, v38, v202
	v_sub_f32_e32 v39, v39, v202
	v_sub_f32_e32 v40, v40, v202
	v_sub_f32_e32 v41, v41, v202
	v_sub_f32_e32 v42, v42, v202
	v_sub_f32_e32 v43, v43, v202
	v_sub_f32_e32 v44, v44, v202
	v_sub_f32_e32 v45, v45, v202
	v_sub_f32_e32 v46, v46, v202
	v_sub_f32_e32 v47, v47, v202
	v_sub_f32_e32 v48, v48, v202
	v_sub_f32_e32 v49, v49, v202
	v_sub_f32_e32 v50, v50, v202
	v_sub_f32_e32 v51, v51, v202
	v_sub_f32_e32 v52, v52, v202
	v_sub_f32_e32 v53, v53, v202
	v_sub_f32_e32 v54, v54, v202
	v_sub_f32_e32 v55, v55, v202
	v_sub_f32_e32 v56, v56, v202
	v_sub_f32_e32 v57, v57, v202
	v_sub_f32_e32 v58, v58, v202
	v_sub_f32_e32 v59, v59, v202
	v_sub_f32_e32 v60, v60, v202
	v_sub_f32_e32 v61, v61, v202
	v_sub_f32_e32 v62, v62, v202
	v_sub_f32_e32 v63, v63, v202
	v_sub_f32_e32 v176, 0, v195
	v_sub_f32_e32 v177, 0, v195
	v_sub_f32_e32 v178, 0, v195
	v_sub_f32_e32 v179, 0, v195
	v_sub_f32_e32 v180, 0, v195
	v_sub_f32_e32 v181, 0, v195
	v_sub_f32_e32 v182, 0, v195
	v_sub_f32_e32 v183, 0, v195
	v_sub_f32_e32 v184, 0, v195
	v_sub_f32_e32 v185, 0, v195
	v_sub_f32_e32 v186, 0, v195
	v_sub_f32_e32 v187, 0, v195
	v_sub_f32_e32 v188, 0, v195
	v_sub_f32_e32 v189, 0, v195
	v_sub_f32_e32 v190, 0, v195
	v_sub_f32_e32 v191, 0, v195
	v_mov_b32_e32 v220, 0x41000000
	v_mov_b32_e32 v167, 0x43800000
	s_mov_b32 s101, 1

; #define MFMA(a, b, c) __builtin_amdgcn_mfma_f32_32x32x16_bf16((a), (b), (c), 0, 0, 0)
; DI float fexp2(float x) { return __builtin_amdgcn_exp2f(x); }
; DI f32x16 zero16() { f32x16 z; for (int i = 0; i < 16; ++i) z[i] = 0.f; return z; }
; DI void phase_attn(const Params& p, int hf, bool skipctx, char* smem, int& rot) {
;     ...
;       const char* sk = smem + buf * STG + half * 64 * KROW; const char* sv = smem + buf * STG + KB_ + half * 128;
;       f32x16 st[2]; st[0] = zero16(); st[1] = zero16();
;       {
;         bf16x8 kf[2][6];
; #pragma unroll
;         for (int kb = 0; kb < 2; ++kb)
; #pragma unroll
;           for (int ks = 0; ks < 6; ++ks) kf[kb][ks] = *(const bf16x8*)(sk + (kb * 32 + r) * KROW + (ks * 16 + h * 8) * 2);
;         __builtin_amdgcn_sched_barrier(0);
; #pragma unroll
;         for (int ks = 0; ks < 6; ++ks)
; #pragma unroll
;           for (int kb = 0; kb < 2; ++kb) st[kb] = MFMA(kf[kb][ks], qf[ks], st[kb]);
;         __builtin_amdgcn_sched_barrier(0);
;       }
;       bf16x8 vf[2][2][2];
; #pragma unroll
;       for (int kb = 0; kb < 2; ++kb)
; #pragma unroll
;         for (int s2 = 0; s2 < 2; ++s2)
; #pragma unroll
;           for (int dvb = 0; dvb < 2; ++dvb) {
;             const char* vp = sv + (dvb * 32 + r) * VROW + (kb * 32 + 16 * s2 + 4 * h) * 2;
;             const s16x4 lo = *(const s16x4*)vp, hi = *(const s16x4*)(vp + 16);
;             vf[kb][s2][dvb] = __builtin_shufflevector(lo, hi, 0, 1, 2, 3, 4, 5, 6, 7);
;           }
;       float mx = st[0][0];
; #pragma unroll
;       for (int i = 0; i < 16; ++i) { mx = fmaxf(mx, st[0][i]); mx = fmaxf(mx, st[1][i]); }
;       if (__any(mx > m_run + 8.f)) {
;         mx = fmaxf(mx, __shfl_xor(mx, 32));
;         const float m_new = fmaxf(m_run, mx);
;         const float alpha = fexp2(m_run - m_new);
;         m_run = m_new;
;         l_run *= alpha;
; #pragma unroll
;         for (int i = 0; i < 16; ++i) { o[0][i] *= alpha; o[1][i] *= alpha; }
;       }
.Lsc0_fb3:
	ds_read_b128 v[36:39], v210 offset:57344
	ds_read_b128 v[132:135], v210 offset:57376
	ds_read_b128 v[136:139], v210 offset:57408
	ds_read_b128 v[140:143], v210 offset:57440
	ds_read_b128 v[144:147], v210 offset:57472
	ds_read_b128 v[148:151], v210 offset:57504
	ds_read_b128 v[40:43], v210 offset:64000
	ds_read_b128 v[152:155], v210 offset:64032
	ds_read_b128 v[156:159], v210 offset:64064
	ds_read_b128 v[216:219], v210 offset:64096
	ds_read_b128 v[234:237], v210 offset:64128
	ds_read_b128 v[238:241], v210 offset:64160
	s_waitcnt lgkmcnt(0)
	s_waitcnt lgkmcnt(11)
	v_mfma_f32_32x32x16_bf16 v[48:63], v[36:39], v[64:67], v[176:191]
	s_waitcnt lgkmcnt(5)
	v_mfma_f32_32x32x16_bf16 v[32:47], v[40:43], v[64:67], v[176:191]
	v_mfma_f32_32x32x16_bf16 v[48:63], v[132:135], v[68:71], v[48:63]
	s_waitcnt lgkmcnt(4)
	v_mfma_f32_32x32x16_bf16 v[32:47], v[152:155], v[68:71], v[32:47]
	v_mfma_f32_32x32x16_bf16 v[48:63], v[136:139], v[72:75], v[48:63]
	s_waitcnt lgkmcnt(3)
	v_mfma_f32_32x32x16_bf16 v[32:47], v[156:159], v[72:75], v[32:47]
	v_mfma_f32_32x32x16_bf16 v[48:63], v[140:143], v[88:91], v[48:63]
	s_waitcnt lgkmcnt(2)
	v_mfma_f32_32x32x16_bf16 v[32:47], v[216:219], v[88:91], v[32:47]
	v_mfma_f32_32x32x16_bf16 v[48:63], v[144:147], v[96:99], v[48:63]
	s_waitcnt lgkmcnt(1)
	v_mfma_f32_32x32x16_bf16 v[32:47], v[234:237], v[96:99], v[32:47]
	v_mfma_f32_32x32x16_bf16 v[48:63], v[148:151], v[100:103], v[48:63]
	s_waitcnt lgkmcnt(0)
	v_mfma_f32_32x32x16_bf16 v[32:47], v[238:241], v[100:103], v[32:47]
	s_nop 3
	ds_read_b128 v[152:155], v211 offset:52864
	ds_read_b128 v[156:159], v211 offset:44160
	ds_read_b128 v[148:151], v211 offset:44192
	ds_read_b128 v[144:147], v211 offset:52896
	ds_read_b128 v[140:143], v211 offset:44224
	ds_read_b128 v[136:139], v211 offset:52928
	ds_read_b128 v[132:135], v211 offset:44256
	ds_read_b128 v[128:131], v211 offset:52960
	v_max3_f32 v195, v32, v48, v49
	v_max_f32_e32 v195, v195, v33
	v_max3_f32 v195, v195, v50, v34
	v_max3_f32 v195, v195, v51, v35
	v_max3_f32 v195, v195, v52, v36
	v_max3_f32 v195, v195, v53, v37
	v_max3_f32 v195, v195, v54, v38
	v_max3_f32 v195, v195, v55, v39
	v_max3_f32 v195, v195, v56, v40
	v_max3_f32 v195, v195, v57, v41
	v_max3_f32 v195, v195, v58, v42
	v_max3_f32 v195, v195, v59, v43
	v_max3_f32 v195, v195, v60, v44
	v_max3_f32 v195, v195, v61, v45
	v_max3_f32 v195, v195, v62, v46
	v_max3_f32 v215, v195, v63, v47
	v_cmp_gt_f32_e32 vcc, v215, v220
	s_cbranch_vccz .Lsc0_c3_LBB0_807
	v_sub_f32_e32 v215, v215, v176
	v_cmp_lt_i32_e32 vcc, v224, v207
	s_nop 1
	v_cndmask_b32_e32 v195, v205, v224, vcc
	v_lshlrev_b32_e32 v195, 2, v195
	ds_bpermute_b32 v195, v195, v215
	s_waitcnt lgkmcnt(0)
	v_max3_f32 v195, v212, v215, v195
	v_sub_f32_e32 v200, v212, v195
	v_exp_f32_e32 v200, v200
	v_mov_b32_e32 v212, v195
	v_mul_f32_e32 v213, v213, v200
	v_pk_mul_f32 v[30:31], v[30:31], v[200:201] op_sel_hi:[1,0]
	v_pk_mul_f32 v[28:29], v[28:29], v[200:201] op_sel_hi:[1,0]
	v_pk_mul_f32 v[26:27], v[26:27], v[200:201] op_sel_hi:[1,0]
	v_pk_mul_f32 v[24:25], v[24:25], v[200:201] op_sel_hi:[1,0]
	v_pk_mul_f32 v[22:23], v[22:23], v[200:201] op_sel_hi:[1,0]
	v_pk_mul_f32 v[20:21], v[20:21], v[200:201] op_sel_hi:[1,0]
	v_pk_mul_f32 v[18:19], v[18:19], v[200:201] op_sel_hi:[1,0]
	v_pk_mul_f32 v[16:17], v[16:17], v[200:201] op_sel_hi:[1,0]
	v_pk_mul_f32 v[14:15], v[14:15], v[200:201] op_sel_hi:[1,0]
	v_pk_mul_f32 v[12:13], v[12:13], v[200:201] op_sel_hi:[1,0]
	v_pk_mul_f32 v[10:11], v[10:11], v[200:201] op_sel_hi:[1,0]
	v_pk_mul_f32 v[8:9], v[8:9], v[200:201] op_sel_hi:[1,0]
	v_pk_mul_f32 v[6:7], v[6:7], v[200:201] op_sel_hi:[1,0]
	v_pk_mul_f32 v[4:5], v[4:5], v[200:201] op_sel_hi:[1,0]
	v_pk_mul_f32 v[2:3], v[2:3], v[200:201] op_sel_hi:[1,0]
	v_pk_mul_f32 v[0:1], v[0:1], v[200:201] op_sel_hi:[1,0]
	v_add_f32_e32 v202, v195, v176
	v_sub_f32_e32 v32, v32, v202
	v_sub_f32_e32 v33, v33, v202
	v_sub_f32_e32 v34, v34, v202
	v_sub_f32_e32 v35, v35, v202
	v_sub_f32_e32 v36, v36, v202
	v_sub_f32_e32 v37, v37, v202
	v_sub_f32_e32 v38, v38, v202
	v_sub_f32_e32 v39, v39, v202
	v_sub_f32_e32 v40, v40, v202
	v_sub_f32_e32 v41, v41, v202
	v_sub_f32_e32 v42, v42, v202
	v_sub_f32_e32 v43, v43, v202
	v_sub_f32_e32 v44, v44, v202
	v_sub_f32_e32 v45, v45, v202
	v_sub_f32_e32 v46, v46, v202
	v_sub_f32_e32 v47, v47, v202
	v_sub_f32_e32 v48, v48, v202
	v_sub_f32_e32 v49, v49, v202
	v_sub_f32_e32 v50, v50, v202
	v_sub_f32_e32 v51, v51, v202
	v_sub_f32_e32 v52, v52, v202
	v_sub_f32_e32 v53, v53, v202
	v_sub_f32_e32 v54, v54, v202
	v_sub_f32_e32 v55, v55, v202
	v_sub_f32_e32 v56, v56, v202
	v_sub_f32_e32 v57, v57, v202
	v_sub_f32_e32 v58, v58, v202
	v_sub_f32_e32 v59, v59, v202
	v_sub_f32_e32 v60, v60, v202
	v_sub_f32_e32 v61, v61, v202
	v_sub_f32_e32 v62, v62, v202
	v_sub_f32_e32 v63, v63, v202
	v_sub_f32_e32 v176, 0, v195
	v_sub_f32_e32 v177, 0, v195
	v_sub_f32_e32 v178, 0, v195
	v_sub_f32_e32 v179, 0, v195
	v_sub_f32_e32 v180, 0, v195
	v_sub_f32_e32 v181, 0, v195
	v_sub_f32_e32 v182, 0, v195
	v_sub_f32_e32 v183, 0, v195
	v_sub_f32_e32 v184, 0, v195
	v_sub_f32_e32 v185, 0, v195
	v_sub_f32_e32 v186, 0, v195
	v_sub_f32_e32 v187, 0, v195
	v_sub_f32_e32 v188, 0, v195
	v_sub_f32_e32 v189, 0, v195
	v_sub_f32_e32 v190, 0, v195
	v_sub_f32_e32 v191, 0, v195
	v_mov_b32_e32 v220, 0x41000000
	v_mov_b32_e32 v167, 0x43800000
	s_mov_b32 s101, 1

; DI float bflo(unsigned u) { return __uint_as_float(u << 16); }
; DI float bfhi(unsigned u) { return __uint_as_float(u & 0xffff0000u); }
; DI f32x16 zero16() { f32x16 z; for (int i = 0; i < 16; ++i) z[i] = 0.f; return z; }
; DI void phase_attn(const Params& p, int hf, bool skipctx, char* smem, int& rot) {
;     ...
;       uint4 qu[6];
; #pragma unroll
;       for (int ks = 0; ks < 6; ++ks) qu[ks] = *(const uint4*)(Qb + tq * 768 + head * 96 + ks * 16 + h * 8);
; #pragma unroll
;       for (int ks = 0; ks < 4; ++ks) {
;         const uint4 u = qu[ks];
;         qf[ks] = pack8(bflo(u.x) * QSCALE, bfhi(u.x) * QSCALE, bflo(u.y) * QSCALE, bfhi(u.y) * QSCALE, bflo(u.z) * QSCALE, bfhi(u.z) * QSCALE, bflo(u.w) * QSCALE, bfhi(u.w) * QSCALE);
;       }
;       const unsigned a1[4] = {qu[4].x, qu[4].y, qu[4].z, qu[4].w}, a2[4] = {qu[5].x, qu[5].y, qu[5].z, qu[5].w};
;       float o1[8], o2[8];
;       const int sq_ = s0 + w * 32 + r;
; #pragma unroll
;       for (int e = 0; e < 8; ++e) {
;         const float x1 = ((e & 1) ? bfhi(a1[e >> 1]) : bflo(a1[e >> 1])) * QSCALE;
;         const float x2 = ((e & 1) ? bfhi(a2[e >> 1]) : bflo(a2[e >> 1])) * QSCALE;
;         float cs = 1.f, sn = 0.f;
;         if (sq_ >= LC) { cs = axc[(sq_ - LC) * 16 + 8 * h + e]; sn = axs[(sq_ - LC) * 16 + 8 * h + e]; }
;         o1[e] = x1 * cs - x2 * sn; o2[e] = x1 * sn + x2 * cs;
;       }
;       qf[4] = pack8(o1[0], o1[1], o1[2], o1[3], o1[4], o1[5], o1[6], o1[7]);
;       qf[5] = pack8(o2[0], o2[1], o2[2], o2[3], o2[4], o2[5], o2[6], o2[7]);
;     }
;     const bf16_t* Kg = Kb + (size_t)(bl * 8 + head) * S * 96;
;     const bf16_t* Vg = VTb + (size_t)(bl * 8 + head) * 64 * S;
;     f32x16 o[2]; o[0] = zero16(); o[1] = zero16();
;     float m_run = -1e30f, l_run = 0.f;
;     uint4 ak0, ak1, ak2, av0, av1, bk0, bk1, bk2, bv0, bv1;
;     const int kr0 = tid / 12, kc0 = tid - kr0 * 12, kr1 = (tid + 512) / 12, kc1 = (tid + 512) - kr1 * 12, kr2 = (tid + 1024) / 12, kc2 = (tid + 1024) - kr2 * 12;
.LBB0_1059:
	s_or_b64 exec, exec, s[26:27]
	s_waitcnt vmcnt(0)
	v_lshlrev_b32_e32 v27, 16, v23
	v_lshlrev_b32_e32 v26, 16, v19
	v_pk_mul_f32 v[26:27], v[26:27], s[48:49] op_sel_hi:[1,0]
	v_lshlrev_b32_e32 v47, 16, v22
	v_pk_mul_f32 v[28:29], v[26:27], v[30:31] op_sel:[0,1] op_sel_hi:[1,0]
	v_pk_mul_f32 v[26:27], v[26:27], v[30:31]
	v_and_b32_e32 v30, 0xffff0000, v19
	v_lshlrev_b32_e32 v46, 16, v18
	v_and_b32_e32 v19, 0xffff0000, v22
	v_and_b32_e32 v18, 0xffff0000, v18
	v_and_b32_e32 v31, 0xffff0000, v23
	v_pk_mul_f32 v[46:47], v[46:47], s[48:49] op_sel_hi:[1,0]
	v_pk_mul_f32 v[22:23], v[18:19], s[48:49] op_sel_hi:[1,0]
	v_pk_mul_f32 v[48:49], v[46:47], v[42:43] op_sel:[0,1] op_sel_hi:[1,0]
	v_pk_mul_f32 v[42:43], v[46:47], v[42:43]
	v_pk_mul_f32 v[18:19], v[22:23], v[40:41] op_sel:[0,1] op_sel_hi:[1,0]
	v_pk_mul_f32 v[22:23], v[22:23], v[40:41]
	v_mov_b32_e32 v40, v42
	v_mov_b32_e32 v41, v22
	v_mov_b32_e32 v22, v43
	v_pk_add_f32 v[22:23], v[40:41], v[22:23]
	v_lshlrev_b32_e32 v41, 16, v21
	v_lshlrev_b32_e32 v40, 16, v17
	v_pk_mul_f32 v[40:41], v[40:41], s[48:49] op_sel_hi:[1,0]
	v_mov_b32_e32 v46, v48
	v_mov_b32_e32 v47, v18
	v_mov_b32_e32 v18, v49
	v_pk_mul_f32 v[42:43], v[40:41], v[32:33] op_sel:[0,1] op_sel_hi:[1,0]
	v_pk_mul_f32 v[40:41], v[40:41], v[32:33]
	v_and_b32_e32 v33, 0xffff0000, v21
	v_and_b32_e32 v32, 0xffff0000, v17
	v_pk_add_f32 v[18:19], v[46:47], v[18:19] neg_lo:[0,1] neg_hi:[0,1]
	v_pk_mul_f32 v[46:47], v[32:33], s[48:49] op_sel_hi:[1,0]
	v_mov_b32_e32 v48, v42
	v_pk_mul_f32 v[32:33], v[46:47], v[34:35] op_sel:[0,1] op_sel_hi:[1,0]
	v_pk_mul_f32 v[34:35], v[46:47], v[34:35]
	v_mov_b32_e32 v49, v32
	v_mov_b32_e32 v32, v43
	v_mov_b32_e32 v42, v40
	v_mov_b32_e32 v43, v34
	v_mov_b32_e32 v34, v41
	v_lshlrev_b32_e32 v41, 16, v20
	v_lshlrev_b32_e32 v40, 16, v16
	v_and_b32_e32 v17, 0xffff0000, v20
	v_and_b32_e32 v16, 0xffff0000, v16
	v_pk_mul_f32 v[40:41], v[40:41], s[48:49] op_sel_hi:[1,0]
	v_pk_mul_f32 v[20:21], v[16:17], s[48:49] op_sel_hi:[1,0]
	v_pk_add_f32 v[34:35], v[42:43], v[34:35]
	v_pk_mul_f32 v[42:43], v[40:41], v[38:39] op_sel:[0,1] op_sel_hi:[1,0]
	v_pk_mul_f32 v[38:39], v[40:41], v[38:39]
	v_pk_mul_f32 v[16:17], v[20:21], v[36:37] op_sel:[0,1] op_sel_hi:[1,0]
	v_pk_mul_f32 v[20:21], v[20:21], v[36:37]
	v_mov_b32_e32 v36, v38
	v_mov_b32_e32 v37, v20
	v_mov_b32_e32 v20, v39
	v_pk_add_f32 v[20:21], v[36:37], v[20:21]
	v_lshlrev_b32_e32 v36, 16, v12
	v_and_b32_e32 v37, 0xffff0000, v12
	v_lshlrev_b32_e32 v12, 16, v13
	v_and_b32_e32 v13, 0xffff0000, v13
	v_pk_mul_f32 v[12:13], v[12:13], s[48:49] op_sel_hi:[1,0]
	v_lshlrev_b32_e32 v38, 16, v14
	v_cvt_pk_bf16_f32 v65, v12, v13
	v_lshlrev_b32_e32 v12, 16, v8
	v_and_b32_e32 v13, 0xffff0000, v8
	v_lshlrev_b32_e32 v8, 16, v9
	v_and_b32_e32 v9, 0xffff0000, v9
	v_pk_mul_f32 v[8:9], v[8:9], s[48:49] op_sel_hi:[1,0]
	v_and_b32_e32 v39, 0xffff0000, v14
	v_cvt_pk_bf16_f32 v69, v8, v9
	v_lshlrev_b32_e32 v8, 16, v4
	v_and_b32_e32 v9, 0xffff0000, v4
	v_lshlrev_b32_e32 v4, 16, v5
	v_and_b32_e32 v5, 0xffff0000, v5
	v_lshlrev_b32_e32 v14, 16, v15
	v_and_b32_e32 v15, 0xffff0000, v15
	v_pk_mul_f32 v[4:5], v[4:5], s[48:49] op_sel_hi:[1,0]
	s_mov_b32 s29, 0x2aaaaaab
	v_pk_mul_f32 v[14:15], v[14:15], s[48:49] op_sel_hi:[1,0]
	v_cvt_pk_bf16_f32 v73, v4, v5
	v_mul_hi_i32 v4, v160, s29
	v_cvt_pk_bf16_f32 v67, v14, v15
	v_lshlrev_b32_e32 v14, 16, v10
	v_and_b32_e32 v15, 0xffff0000, v10
	v_lshlrev_b32_e32 v10, 16, v11
	v_and_b32_e32 v11, 0xffff0000, v11
	v_lshrrev_b32_e32 v5, 31, v4
	v_ashrrev_i32_e32 v4, 1, v4
	v_pk_mul_f32 v[10:11], v[10:11], s[48:49] op_sel_hi:[1,0]
	v_add_u32_e32 v45, v4, v5
	v_cvt_pk_bf16_f32 v71, v10, v11
	v_lshlrev_b32_e32 v10, 16, v6
	v_and_b32_e32 v11, 0xffff0000, v6
	v_lshlrev_b32_e32 v6, 16, v7
	v_and_b32_e32 v7, 0xffff0000, v7
	v_mad_u64_u32 v[4:5], s[38:39], v45, -12, v[160:161]
	v_add_u32_e32 v164, 0x200, v160
	v_pk_mul_f32 v[6:7], v[6:7], s[48:49] op_sel_hi:[1,0]
	v_mul_hi_i32 v5, v164, s29
	v_cvt_pk_bf16_f32 v75, v6, v7
	v_lshrrev_b32_e32 v6, 31, v5
	v_ashrrev_i32_e32 v5, 1, v5
	s_mul_i32 s15, s4, 0xcc000
	v_add_u32_e32 v5, v5, v6
	v_pk_mul_f32 v[38:39], v[38:39], s[48:49] op_sel_hi:[1,0]
	v_pk_mul_f32 v[14:15], v[14:15], s[48:49] op_sel_hi:[1,0]
	s_mul_hi_i32 s5, s4, 0xcc000
	s_add_u32 s26, s90, s15
	v_mad_u64_u32 v[6:7], s[38:39], v5, -12, v[164:165]
	v_add_u32_e32 v162, 0x400, v160
	v_cvt_pk_bf16_f32 v66, v38, v39
	v_cvt_pk_bf16_f32 v70, v14, v15
	v_pk_mul_f32 v[8:9], v[8:9], s[48:49] op_sel_hi:[1,0]
	v_pk_mul_f32 v[10:11], v[10:11], s[48:49] op_sel_hi:[1,0]
	s_addc_u32 s27, s91, s5
	v_mul_hi_i32 v7, v162, s29
	v_lshlrev_b32_e32 v14, 3, v4
	v_lshlrev_b32_e32 v38, 3, v6
	v_pk_mul_f32 v[36:37], v[36:37], s[48:49] op_sel_hi:[1,0]
	v_pk_mul_f32 v[12:13], v[12:13], s[48:49] op_sel_hi:[1,0]
	v_cvt_pk_bf16_f32 v72, v8, v9
	v_cvt_pk_bf16_f32 v74, v10, v11
	v_lshrrev_b32_e32 v8, 31, v7
	v_ashrrev_i32_e32 v7, 1, v7
	v_mov_b64_e32 v[10:11], s[26:27]
	v_ashrrev_i32_e32 v15, 31, v14
	v_ashrrev_i32_e32 v39, 31, v38
	v_cvt_pk_bf16_f32 v64, v36, v37
	v_cvt_pk_bf16_f32 v68, v12, v13
	v_add_u32_e32 v7, v7, v8
	v_mad_i64_i32 v[12:13], s[26:27], v45, s17, v[10:11]
	v_lshlrev_b64 v[14:15], 1, v[14:15]
	v_mad_i64_i32 v[36:37], s[26:27], v5, s17, v[10:11]
	v_lshlrev_b64 v[38:39], 1, v[38:39]
	v_mad_u64_u32 v[8:9], s[38:39], v7, -12, v[162:163]
	v_lshl_add_u64 v[12:13], v[12:13], 0, v[14:15]
	v_lshl_add_u64 v[36:37], v[36:37], 0, v[38:39]
	s_barrier
; DI float bflo(unsigned u) { return __uint_as_float(u << 16); }
; DI float bfhi(unsigned u) { return __uint_as_float(u & 0xffff0000u); }
; DI f32x16 zero16() { f32x16 z; for (int i = 0; i < 16; ++i) z[i] = 0.f; return z; }
; DI void phase_attn(const Params& p, int hf, bool skipctx, char* smem, int& rot) {
;     ...
;       const unsigned a1[4] = {qu[4].x, qu[4].y, qu[4].z, qu[4].w}, a2[4] = {qu[5].x, qu[5].y, qu[5].z, qu[5].w};
;       float o1[8], o2[8];
;       const int sq_ = s0 + w * 32 + r;
; #pragma unroll
;       for (int e = 0; e < 8; ++e) {
;         const float x1 = ((e & 1) ? bfhi(a1[e >> 1]) : bflo(a1[e >> 1])) * QSCALE;
;         const float x2 = ((e & 1) ? bfhi(a2[e >> 1]) : bflo(a2[e >> 1])) * QSCALE;
;         float cs = 1.f, sn = 0.f;
;         if (sq_ >= LC) { cs = axc[(sq_ - LC) * 16 + 8 * h + e]; sn = axs[(sq_ - LC) * 16 + 8 * h + e]; }
;         o1[e] = x1 * cs - x2 * sn; o2[e] = x1 * sn + x2 * cs;
;       }
;       qf[4] = pack8(o1[0], o1[1], o1[2], o1[3], o1[4], o1[5], o1[6], o1[7]);
;       qf[5] = pack8(o2[0], o2[1], o2[2], o2[3], o2[4], o2[5], o2[6], o2[7]);
;     }
;     const bf16_t* Kg = Kb + (size_t)(bl * 8 + head) * S * 96;
;     const bf16_t* Vg = VTb + (size_t)(bl * 8 + head) * 64 * S;
;     f32x16 o[2]; o[0] = zero16(); o[1] = zero16();
;     float m_run = -1e30f, l_run = 0.f;
;     uint4 ak0, ak1, ak2, av0, av1, bk0, bk1, bk2, bv0, bv1;
;     const int kr0 = tid / 12, kc0 = tid - kr0 * 12, kr1 = (tid + 512) / 12, kc1 = (tid + 512) - kr1 * 12, kr2 = (tid + 1024) / 12, kc2 = (tid + 1024) - kr2 * 12;
;     const int vr0 = tid >> 4, vr1 = (tid + 512) >> 4, vc = tid & 15;
	global_load_dwordx4 v[76:79], v[12:13], off
	global_load_dwordx4 v[80:83], v[36:37], off
	v_lshlrev_b32_e32 v36, 3, v8
	s_mul_i32 s15, s4, 0x88000
	v_readlane_b32 s36, v252, 5
	v_ashrrev_i32_e32 v37, 31, v36
	s_mul_hi_i32 s5, s4, 0x88000
	v_readlane_b32 s37, v252, 6
	s_add_u32 s36, s36, s15
	v_mad_i64_i32 v[12:13], s[26:27], v7, s17, v[10:11]
	v_lshlrev_b64 v[36:37], 1, v[36:37]
	s_addc_u32 s37, s37, s5
	v_lshl_add_u64 v[12:13], v[12:13], 0, v[36:37]
	v_mov_b32_e32 v40, v42
	v_mov_b32_e32 v41, v16
	v_mov_b32_e32 v16, v43
	v_ashrrev_i32_e32 v9, 4, v160
	v_ashrrev_i32_e32 v50, 4, v164
	global_load_dwordx4 v[84:87], v[12:13], off
	v_mov_b64_e32 v[12:13], s[36:37]
	v_lshlrev_b32_e32 v165, 4, v160
	v_cvt_pk_bf16_f32 v100, v20, v21
	v_add_u32_e32 v20, 0x80, v5
	v_pk_add_f32 v[16:17], v[40:41], v[16:17] neg_lo:[0,1] neg_hi:[0,1]
	v_mad_i64_i32 v[40:41], s[26:27], v9, s16, v[12:13]
	v_and_b32_e32 v42, 0xf0, v165
	v_mov_b32_e32 v43, v221
	v_mad_i64_i32 v[12:13], s[26:27], v50, s16, v[12:13]
	v_cvt_pk_bf16_f32 v98, v18, v19
	v_cvt_pk_bf16_f32 v102, v22, v23
	v_add_u32_e32 v18, 0x80, v45
	v_mad_i64_i32 v[20:21], s[26:27], v20, s17, v[10:11]
	v_add_u32_e32 v22, 0x80, v7
	v_lshl_add_u64 v[40:41], v[40:41], 0, v[42:43]
	v_lshl_add_u64 v[12:13], v[12:13], 0, v[42:43]
	v_mad_i64_i32 v[18:19], s[26:27], v18, s17, v[10:11]
	v_lshl_add_u64 v[20:21], v[20:21], 0, v[38:39]
	v_mad_i64_i32 v[10:11], s[26:27], v22, s17, v[10:11]
	global_load_dwordx4 v[92:95], v[40:41], off
	global_load_dwordx4 v[104:107], v[12:13], off
	v_lshl_add_u64 v[18:19], v[18:19], 0, v[14:15]
	v_lshl_add_u64 v[10:11], v[10:11], 0, v[36:37]
	global_load_dwordx4 v[108:111], v[20:21], off
	global_load_dwordx4 v[116:119], v[10:11], off
	global_load_dwordx4 v[120:123], v[40:41], off offset:256
	global_load_dwordx4 v[112:115], v[18:19], off
	global_load_dwordx4 v[124:127], v[12:13], off offset:256
	v_lshlrev_b32_e32 v46, 16, v0
	v_and_b32_e32 v47, 0xffff0000, v0
	v_lshlrev_b32_e32 v0, 16, v1
	v_and_b32_e32 v1, 0xffff0000, v1
	v_pk_mul_f32 v[30:31], v[30:31], s[48:49] op_sel_hi:[1,0]
	v_pk_add_f32 v[32:33], v[48:49], v[32:33] neg_lo:[0,1] neg_hi:[0,1]
	v_pk_mul_f32 v[0:1], v[0:1], s[48:49] op_sel_hi:[1,0]
	v_lshlrev_b32_e32 v48, 16, v2
	v_and_b32_e32 v49, 0xffff0000, v2
	v_lshlrev_b32_e32 v2, 16, v3
	v_and_b32_e32 v3, 0xffff0000, v3
	v_pk_mul_f32 v[2:3], v[2:3], s[48:49] op_sel_hi:[1,0]
	v_cvt_pk_bf16_f32 v89, v0, v1
	v_pk_mul_f32 v[0:1], v[30:31], v[24:25] op_sel:[0,1] op_sel_hi:[1,0]
	v_cvt_pk_bf16_f32 v91, v2, v3
	v_mov_b32_e32 v2, v28
	v_mov_b32_e32 v3, v0
	v_mov_b32_e32 v0, v29
	v_pk_add_f32 v[0:1], v[2:3], v[0:1] neg_lo:[0,1] neg_hi:[0,1]
	v_pk_mul_f32 v[2:3], v[30:31], v[24:25]
	v_mul_lo_u32 v10, v45, s97
	v_mov_b32_e32 v24, v26
	v_mov_b32_e32 v25, v2
	v_mov_b32_e32 v2, v27
	v_add_u32_e32 v10, 0, v10
	v_lshlrev_b32_e32 v4, 4, v4
	v_pk_add_f32 v[2:3], v[24:25], v[2:3]
	v_add_u32_e32 v176, v10, v4
	v_mul_lo_u32 v4, v5, s97
	v_cvt_pk_bf16_f32 v103, v2, v3
	v_mad_i64_i32 v[2:3], s[26:27], v5, s17, 0
	v_add_u32_e32 v4, 0, v4
	v_lshlrev_b32_e32 v5, 4, v6
	v_cvt_pk_bf16_f32 v96, v16, v17
	v_cvt_pk_bf16_f32 v99, v0, v1
	v_mad_i64_i32 v[0:1], s[26:27], v45, s17, 0
	v_mad_i64_i32 v[16:17], s[26:27], v7, s17, 0
	v_add_u32_e32 v177, v4, v5
	v_mul_lo_u32 v4, v7, s97
	v_add_u32_e32 v4, 0, v4
	v_lshlrev_b32_e32 v5, 4, v8
	s_movk_i32 s26, 0x108
	v_add_u32_e32 v178, v4, v5
	v_mul_lo_u32 v4, v9, s26
	v_add_u32_e32 v5, 0, v4
	s_movk_i32 s27, 0x6800
	v_add3_u32 v179, v5, v42, s27
	v_mul_lo_u32 v5, v50, s26
	v_add_u32_e32 v6, 0, v5
	v_add3_u32 v180, v6, v42, s27
	v_or_b32_e32 v181, 32, v161
	v_or_b32_e32 v182, 64, v161
	v_or_b32_e32 v183, 0x60, v161
	v_readlane_b32 s27, v254, 35
	v_mul_u32_u24_e32 v19, 0x108, v44
	v_mad_u32_u24 v18, v44, s97, 0
	v_add_u32_e32 v21, s27, v4
	v_add_u32_e32 v22, s27, v5
	v_add_u32_e32 v23, s27, v161
	v_add_u32_e32 v24, s27, v181
	v_mov_b32_e32 v4, s27
	v_add_u32_e32 v25, s27, v182
	v_add_u32_e32 v26, s27, v183
	v_readlane_b32 s27, v254, 36
	v_mad_u32_u24 v184, v44, s26, v4
	v_add_u32_e32 v20, 0, v161
	v_mov_b32_e32 v4, s27
	v_mad_u32_u24 v185, v44, s26, v4
	s_add_u32 s26, s15, 0x1a49c300
	v_add_u32_e32 v27, s27, v161
	v_add_u32_e32 v28, s27, v181
	v_add_u32_e32 v29, s27, v182
	v_add_u32_e32 v30, s27, v183
	s_addc_u32 s27, s5, 0
	v_mov_b64_e32 v[4:5], s[26:27]
	v_mad_i64_i32 v[166:167], s[26:27], v9, s16, v[4:5]
	v_mad_i64_i32 v[168:169], s[26:27], v50, s16, v[4:5]
	v_mad_i64_i32 v[4:5], s[26:27], s4, v231, v[16:17]
	v_mad_i64_i32 v[2:3], s[26:27], s4, v231, v[2:3]
	v_mad_i64_i32 v[0:1], s[4:5], s4, v231, v[0:1]
	v_lshl_add_u64 v[174:175], v[0:1], 0, v[14:15]
	v_mov_b32_e32 v14, v221
	v_mov_b32_e32 v15, v221
	v_add_u32_e32 v186, v21, v42
	v_add_u32_e32 v187, v22, v42
	v_add_u32_e32 v188, v23, v19
	v_add_u32_e32 v16, v24, v19
	v_add_u32_e32 v17, v25, v19
	v_add_u32_e32 v21, v26, v19
	v_add_u32_e32 v22, v28, v19
	v_add_u32_e32 v23, v29, v19
	v_add_u32_e32 v24, v30, v19
	v_pk_mul_f32 v[46:47], v[46:47], s[48:49] op_sel_hi:[1,0]
	v_pk_mul_f32 v[48:49], v[48:49], s[48:49] op_sel_hi:[1,0]
	v_lshl_add_u64 v[170:171], v[4:5], 0, v[36:37]
	v_lshl_add_u64 v[172:173], v[2:3], 0, v[38:39]
	v_mov_b32_e32 v0, v221
	v_mov_b32_e32 v1, v221
	v_mov_b32_e32 v2, v221
	v_mov_b32_e32 v3, v221
	v_mov_b32_e32 v4, v221
	v_mov_b32_e32 v5, v221
	v_mov_b32_e32 v6, v221
	v_mov_b32_e32 v7, v221
	v_mov_b32_e32 v8, v221
	v_mov_b32_e32 v9, v221
	v_mov_b32_e32 v10, v221
	v_mov_b32_e32 v11, v221
	v_mov_b32_e32 v12, v221
	v_mov_b32_e32 v13, v221
	v_add_u32_e32 v189, v27, v19
	v_add_u32_e32 v190, v18, v220
	v_add_u32_e32 v191, v20, v19
	v_add_u32_e32 v194, 0x2000, v16
	v_add_u32_e32 v204, 0x2000, v17
	v_add_u32_e32 v206, 0x2000, v21
	v_add_u32_e32 v208, 0x2000, v22
	v_add_u32_e32 v210, 0x2000, v23
	v_add_u32_e32 v211, 0x2000, v24
	v_mov_b64_e32 v[30:31], v[14:15]
	v_cvt_pk_bf16_f32 v88, v46, v47
	v_cvt_pk_bf16_f32 v90, v48, v49
	v_cvt_pk_bf16_f32 v97, v32, v33
	v_cvt_pk_bf16_f32 v101, v34, v35
	v_or_b32_e32 v166, v166, v42
	v_or_b32_e32 v168, v168, v42
	s_mov_b32 s4, 0
	v_mov_b32_e32 v212, 0xf149f2ca
	v_mov_b32_e32 v213, 0
	v_mov_b64_e32 v[28:29], v[12:13]
	v_mov_b64_e32 v[26:27], v[10:11]
	v_mov_b64_e32 v[24:25], v[8:9]
	v_mov_b64_e32 v[22:23], v[6:7]
	v_mov_b64_e32 v[20:21], v[4:5]
	v_mov_b64_e32 v[18:19], v[2:3]
	v_mov_b64_e32 v[16:17], v[0:1]
	v_and_b32_e32 v200, 15, v192
	v_lshrrev_b32_e32 v201, 4, v192
	v_mul_u32_u24_e32 v179, 0x110, v201
	v_lshrrev_b32_e32 v202, 1, v200
	v_lshl_add_u32 v179, v202, 5, v179
	v_and_b32_e32 v202, 1, v200
	v_lshl_add_u32 v179, v202, 3, v179
	v_add_u32_e32 v179, 0x6800, v179
	v_add_u32_e32 v180, 0x2200, v179
	v_add_u32_e32 v186, 0xac00, v179
	v_add_u32_e32 v187, 0xac00, v180
	v_and_b32_e32 v200, 31, v192
	v_bfe_u32 v201, v192, 5, 1
	v_mul_u32_u24_e32 v191, 0x110, v200
	v_lshl_add_u32 v191, v201, 4, v191
	v_add_u32_e32 v191, 0x6800, v191
	s_waitcnt vmcnt(9)
; DI f32x16 zero16() { f32x16 z; for (int i = 0; i < 16; ++i) z[i] = 0.f; return z; }
; DI void phase_attn(const Params& p, int hf, bool skipctx, char* smem, int& rot) {
;     ...
;     f32x16 o[2]; o[0] = zero16(); o[1] = zero16();
;     float m_run = -1e30f, l_run = 0.f;
;     uint4 ak0, ak1, ak2, av0, av1, bk0, bk1, bk2, bv0, bv1;
;     const int kr0 = tid / 12, kc0 = tid - kr0 * 12, kr1 = (tid + 512) / 12, kc1 = (tid + 512) - kr1 * 12, kr2 = (tid + 1024) / 12, kc2 = (tid + 1024) - kr2 * 12;
;     const int vr0 = tid >> 4, vr1 = (tid + 512) >> 4, vc = tid & 15;
;     ...
;     ATT_WRITE(ak0, ak1, ak2, av0, av1, 0);
;     __syncthreads();
	ds_write_b128 v176, v[76:79]
	s_waitcnt vmcnt(8)
	ds_write_b128 v177, v[80:83]
	s_waitcnt vmcnt(7)
	ds_write_b128 v178, v[84:87]
	s_waitcnt vmcnt(6)
	ds_write_b64 v179, v[92:93] offset:0
	ds_write_b64 v179, v[94:95] offset:16
	s_waitcnt vmcnt(5)
	ds_write_b64 v179, v[104:105] offset:8704
	ds_write_b64 v179, v[106:107] offset:8720
	s_waitcnt lgkmcnt(0)
	s_barrier
	v_mov_b32_e32 v194, v176
	v_mov_b32_e32 v204, v177
	v_mov_b32_e32 v206, v178
	v_mov_b32_e32 v208, v179
	v_mov_b32_e32 v210, v190
	v_mov_b32_e32 v211, v191
	v_mov_b32_e32 v220, 0xf149f2ca
	v_mov_b32_e32 v176, 0
	v_mov_b32_e32 v177, 0
	v_mov_b32_e32 v178, 0
	v_mov_b32_e32 v179, 0
	v_mov_b32_e32 v180, 0
	v_mov_b32_e32 v181, 0
	v_mov_b32_e32 v182, 0
	v_mov_b32_e32 v183, 0
	v_mov_b32_e32 v184, 0
	v_mov_b32_e32 v185, 0
	v_mov_b32_e32 v186, 0
	v_mov_b32_e32 v187, 0
	v_mov_b32_e32 v188, 0
	v_mov_b32_e32 v189, 0
	v_mov_b32_e32 v190, 0
	v_mov_b32_e32 v191, 0
	v_add_u32_e32 v170, 0x18b28000, v170
	v_add_u32_e32 v172, 0x18b28000, v172
	v_add_u32_e32 v174, 0x18b28000, v174
	v_mov_b32_e32 v167, 0xbf800000
	s_mov_b32 s101, 0
